# MFMA blocks reordered: k0,k1 of same accumulator issued back-to-back (chain order) in all 4 GEMM K-loops
# speedup vs baseline: 1.0123x; 1.0075x over previous
.LBB0_126:
	s_ashr_i32 s47, s46, 31
	s_lshl_b64 s[18:19], s[46:47], 21
	s_add_u32 s48, s1, s18
	s_addc_u32 s49, s3, s19
	s_and_b64 s[18:19], s[38:39], exec
	s_cselect_b32 s18, s49, s15
	s_cselect_b32 s19, s48, s14
	s_ashr_i32 s45, s44, 31
	s_lshl_b64 s[50:51], s[44:45], 21
	s_add_u32 s50, s24, s50
	s_addc_u32 s51, s25, s51
	s_and_b64 s[52:53], s[38:39], exec
	s_cselect_b32 s45, s51, s13
	s_cselect_b32 s47, s50, s12
	s_add_u32 s52, s14, 0x100080
	s_addc_u32 s53, s15, 0
	s_add_u32 s54, s12, 0x100
	v_mov_b32_e32 v4, 0
	s_addc_u32 s55, s13, 0
	s_mov_b32 s56, -2
	v_mov_b32_e32 v5, v4
	v_mov_b64_e32 v[6:7], v[4:5]
	v_mov_b64_e32 v[8:9], v[4:5]
	v_mov_b64_e32 v[10:11], v[4:5]
	v_mov_b64_e32 v[12:13], v[4:5]
	v_mov_b64_e32 v[14:15], v[4:5]
	v_mov_b64_e32 v[16:17], v[4:5]
	v_mov_b64_e32 v[18:19], v[4:5]
	v_mov_b64_e32 v[20:21], v[4:5]
	v_mov_b64_e32 v[22:23], v[4:5]
	v_mov_b64_e32 v[24:25], v[4:5]
	v_mov_b64_e32 v[26:27], v[4:5]
	v_mov_b64_e32 v[28:29], v[4:5]
	v_mov_b64_e32 v[30:31], v[4:5]
	v_mov_b64_e32 v[32:33], v[4:5]
	v_mov_b64_e32 v[34:35], v[4:5]
	v_mov_b64_e32 v[36:37], v[4:5]
	v_mov_b64_e32 v[38:39], v[4:5]
	v_mov_b64_e32 v[40:41], v[4:5]
	v_mov_b64_e32 v[42:43], v[4:5]
	v_mov_b64_e32 v[44:45], v[4:5]
	v_mov_b64_e32 v[46:47], v[4:5]
	v_mov_b64_e32 v[48:49], v[4:5]
	v_mov_b64_e32 v[50:51], v[4:5]
	v_mov_b64_e32 v[52:53], v[4:5]
	v_mov_b64_e32 v[54:55], v[4:5]
	v_mov_b64_e32 v[56:57], v[4:5]
	v_mov_b64_e32 v[58:59], v[4:5]
	v_mov_b64_e32 v[60:61], v[4:5]
	v_mov_b64_e32 v[62:63], v[4:5]
	v_mov_b64_e32 v[64:65], v[4:5]
	v_mov_b64_e32 v[66:67], v[4:5]
	v_mov_b64_e32 v[68:69], v[4:5]
	v_mov_b64_e32 v[70:71], v[4:5]
	v_mov_b64_e32 v[72:73], v[4:5]
	v_mov_b64_e32 v[74:75], v[4:5]
	v_mov_b64_e32 v[76:77], v[4:5]
	v_mov_b64_e32 v[78:79], v[4:5]
	v_mov_b64_e32 v[80:81], v[4:5]
	v_mov_b64_e32 v[82:83], v[4:5]
	v_mov_b64_e32 v[84:85], v[4:5]
	v_mov_b64_e32 v[86:87], v[4:5]
	v_mov_b64_e32 v[88:89], v[4:5]
	v_mov_b64_e32 v[90:91], v[4:5]
	v_mov_b64_e32 v[92:93], v[4:5]
	v_mov_b64_e32 v[94:95], v[4:5]
	v_mov_b64_e32 v[96:97], v[4:5]
	v_mov_b64_e32 v[98:99], v[4:5]
	v_mov_b64_e32 v[100:101], v[4:5]
	v_mov_b64_e32 v[102:103], v[4:5]
	v_mov_b64_e32 v[104:105], v[4:5]
	v_mov_b64_e32 v[106:107], v[4:5]
	v_mov_b64_e32 v[108:109], v[4:5]
	v_mov_b64_e32 v[110:111], v[4:5]
	v_mov_b64_e32 v[112:113], v[4:5]
	v_mov_b64_e32 v[114:115], v[4:5]
	v_mov_b64_e32 v[116:117], v[4:5]
	v_mov_b64_e32 v[118:119], v[4:5]
	v_mov_b64_e32 v[120:121], v[4:5]
	v_mov_b64_e32 v[122:123], v[4:5]
	v_mov_b64_e32 v[124:125], v[4:5]
	v_mov_b64_e32 v[126:127], v[4:5]
	v_mov_b64_e32 v[128:129], v[4:5]
	v_mov_b64_e32 v[130:131], v[4:5]
.LBB0_127:
	s_add_u32 s12, s52, 0xfff00080
	s_addc_u32 s13, s53, -1
	s_add_i32 s57, 0, 0x10000
	s_cmp_eq_u32 s56, 60
	s_cselect_b32 s15, s18, s13
	s_cselect_b32 s14, s19, s12
	v_add_u32_e32 v142, s57, v143
	s_cselect_b32 s13, s45, s55
	s_cselect_b32 s12, s47, s54
	s_add_i32 s60, 0, 0x14000
	ds_read_b128 v[146:149], v142
	ds_read_b128 v[152:155], v142 offset:1024
	ds_read_b128 v[156:159], v142 offset:2048
	ds_read_b128 v[160:163], v142 offset:3072
	v_add_u32_e32 v142, s60, v143
	ds_read_b128 v[164:167], v142
	ds_read_b128 v[168:171], v142 offset:1024
	ds_read_b128 v[172:175], v142 offset:2048
	ds_read_b128 v[176:179], v142 offset:3072
	v_lshl_add_u64 v[192:193], s[52:53], 0, v[138:139]
	s_add_i32 m0, s27, 0xc000
	ds_read_b128 v[180:183], v151
	ds_read_b128 v[184:187], v151 offset:1024
	ds_read_b128 v[188:191], v151 offset:2048
	ds_read_b128 v[206:209], v151 offset:3072
	ds_read_b128 v[210:213], v151 offset:4096
	ds_read_b128 v[240:243], v151 offset:5120
	ds_read_b128 v[244:247], v151 offset:6144
	ds_read_b128 v[248:251], v151 offset:7168
	global_load_lds_dwordx4 v[192:193], off
	v_lshl_add_u64 v[192:193], s[52:53], 0, v[140:141]
	s_add_i32 m0, s27, 0xe000
	s_nop 0
	global_load_lds_dwordx4 v[192:193], off
	s_waitcnt vmcnt(8)
	s_waitcnt lgkmcnt(0)
	s_barrier
	s_waitcnt lgkmcnt(0)
	v_mfma_f32_16x16x32_bf16 v[128:131], v[146:149], v[180:183], v[128:131]
	v_mfma_f32_16x16x32_bf16 v[128:131], v[152:155], v[184:187], v[128:131]
	v_mfma_f32_16x16x32_bf16 v[124:127], v[156:159], v[180:183], v[124:127]
	v_mfma_f32_16x16x32_bf16 v[124:127], v[160:163], v[184:187], v[124:127]
	v_mfma_f32_16x16x32_bf16 v[112:115], v[146:149], v[188:191], v[112:115]
	v_mfma_f32_16x16x32_bf16 v[112:115], v[152:155], v[206:209], v[112:115]
	v_mfma_f32_16x16x32_bf16 v[108:111], v[156:159], v[188:191], v[108:111]
	v_mfma_f32_16x16x32_bf16 v[108:111], v[160:163], v[206:209], v[108:111]
	v_mfma_f32_16x16x32_bf16 v[96:99], v[146:149], v[210:213], v[96:99]
	v_mfma_f32_16x16x32_bf16 v[96:99], v[152:155], v[240:243], v[96:99]
	v_mfma_f32_16x16x32_bf16 v[92:95], v[156:159], v[210:213], v[92:95]
	v_mfma_f32_16x16x32_bf16 v[92:95], v[160:163], v[240:243], v[92:95]
	v_mfma_f32_16x16x32_bf16 v[80:83], v[146:149], v[244:247], v[80:83]
	v_mfma_f32_16x16x32_bf16 v[80:83], v[152:155], v[248:251], v[80:83]
	v_mfma_f32_16x16x32_bf16 v[76:79], v[156:159], v[244:247], v[76:79]
	v_mfma_f32_16x16x32_bf16 v[76:79], v[160:163], v[248:251], v[76:79]
	v_mfma_f32_16x16x32_bf16 v[120:123], v[164:167], v[180:183], v[120:123]
	v_mfma_f32_16x16x32_bf16 v[120:123], v[168:171], v[184:187], v[120:123]
	v_mfma_f32_16x16x32_bf16 v[116:119], v[172:175], v[180:183], v[116:119]
	v_mfma_f32_16x16x32_bf16 v[116:119], v[176:179], v[184:187], v[116:119]
	v_mfma_f32_16x16x32_bf16 v[104:107], v[164:167], v[188:191], v[104:107]
	v_mfma_f32_16x16x32_bf16 v[104:107], v[168:171], v[206:209], v[104:107]
	v_mfma_f32_16x16x32_bf16 v[100:103], v[172:175], v[188:191], v[100:103]
	v_mfma_f32_16x16x32_bf16 v[100:103], v[176:179], v[206:209], v[100:103]
	v_mfma_f32_16x16x32_bf16 v[88:91], v[164:167], v[210:213], v[88:91]
	v_mfma_f32_16x16x32_bf16 v[88:91], v[168:171], v[240:243], v[88:91]
	v_mfma_f32_16x16x32_bf16 v[84:87], v[172:175], v[210:213], v[84:87]
	v_mfma_f32_16x16x32_bf16 v[84:87], v[176:179], v[240:243], v[84:87]
	v_mfma_f32_16x16x32_bf16 v[72:75], v[164:167], v[244:247], v[72:75]
	v_mfma_f32_16x16x32_bf16 v[72:75], v[168:171], v[248:251], v[72:75]
	v_mfma_f32_16x16x32_bf16 v[68:71], v[172:175], v[244:247], v[68:71]
	v_mfma_f32_16x16x32_bf16 v[68:71], v[176:179], v[248:251], v[68:71]
	s_barrier
	s_add_i32 s57, s57, s26
	v_lshl_add_u64 v[192:193], s[12:13], 0, v[2:3]
	s_mov_b32 m0, s57
	ds_read_b128 v[180:183], v151 offset:16384
	ds_read_b128 v[184:187], v151 offset:17408
	ds_read_b128 v[188:191], v151 offset:18432
	ds_read_b128 v[206:209], v151 offset:19456
	ds_read_b128 v[210:213], v151 offset:20480
	ds_read_b128 v[240:243], v151 offset:21504
	ds_read_b128 v[244:247], v151 offset:22528
	ds_read_b128 v[248:251], v151 offset:23552
	global_load_lds_dwordx4 v[192:193], off
	s_add_i32 m0, s57, 0x2000
	s_add_u32 s58, s12, 0x100000
	v_lshl_add_u64 v[214:215], s[12:13], 0, v[132:133]
	s_addc_u32 s59, s13, 0
	s_add_i32 s57, s60, s26
	global_load_lds_dwordx4 v[214:215], off
	v_lshl_add_u64 v[224:225], s[58:59], 0, v[2:3]
	s_mov_b32 m0, s57
	v_lshl_add_u64 v[226:227], s[14:15], 0, v[134:135]
	global_load_lds_dwordx4 v[224:225], off
	v_lshl_add_u64 v[224:225], s[58:59], 0, v[132:133]
	s_add_i32 m0, s57, 0x2000
	s_nop 0
	global_load_lds_dwordx4 v[224:225], off
	v_lshl_add_u64 v[224:225], s[14:15], 0, v[136:137]
	s_mov_b32 m0, s27
	s_nop 0
	global_load_lds_dwordx4 v[224:225], off
	s_mov_b32 m0, s28
	s_nop 0
	global_load_lds_dwordx4 v[226:227], off
	s_waitcnt vmcnt(8)
	s_waitcnt lgkmcnt(0)
	s_barrier
	s_waitcnt lgkmcnt(0)
	v_mfma_f32_16x16x32_bf16 v[64:67], v[146:149], v[180:183], v[64:67]
	v_mfma_f32_16x16x32_bf16 v[64:67], v[152:155], v[184:187], v[64:67]
	v_mfma_f32_16x16x32_bf16 v[60:63], v[156:159], v[180:183], v[60:63]
	v_mfma_f32_16x16x32_bf16 v[60:63], v[160:163], v[184:187], v[60:63]
	v_mfma_f32_16x16x32_bf16 v[52:55], v[146:149], v[188:191], v[52:55]
	v_mfma_f32_16x16x32_bf16 v[52:55], v[152:155], v[206:209], v[52:55]
	v_mfma_f32_16x16x32_bf16 v[44:47], v[156:159], v[188:191], v[44:47]
	v_mfma_f32_16x16x32_bf16 v[44:47], v[160:163], v[206:209], v[44:47]
	v_mfma_f32_16x16x32_bf16 v[36:39], v[146:149], v[210:213], v[36:39]
	v_mfma_f32_16x16x32_bf16 v[36:39], v[152:155], v[240:243], v[36:39]
	v_mfma_f32_16x16x32_bf16 v[28:31], v[156:159], v[210:213], v[28:31]
	v_mfma_f32_16x16x32_bf16 v[28:31], v[160:163], v[240:243], v[28:31]
	v_mfma_f32_16x16x32_bf16 v[20:23], v[146:149], v[244:247], v[20:23]
	v_mfma_f32_16x16x32_bf16 v[20:23], v[152:155], v[248:251], v[20:23]
	v_mfma_f32_16x16x32_bf16 v[12:15], v[156:159], v[244:247], v[12:15]
	v_mfma_f32_16x16x32_bf16 v[12:15], v[160:163], v[248:251], v[12:15]
	v_mfma_f32_16x16x32_bf16 v[56:59], v[164:167], v[180:183], v[56:59]
	v_mfma_f32_16x16x32_bf16 v[56:59], v[168:171], v[184:187], v[56:59]
	v_mfma_f32_16x16x32_bf16 v[48:51], v[172:175], v[180:183], v[48:51]
	v_mfma_f32_16x16x32_bf16 v[48:51], v[176:179], v[184:187], v[48:51]
	v_mfma_f32_16x16x32_bf16 v[40:43], v[164:167], v[188:191], v[40:43]
	v_mfma_f32_16x16x32_bf16 v[40:43], v[168:171], v[206:209], v[40:43]
	v_mfma_f32_16x16x32_bf16 v[32:35], v[172:175], v[188:191], v[32:35]
	v_mfma_f32_16x16x32_bf16 v[32:35], v[176:179], v[206:209], v[32:35]
	v_mfma_f32_16x16x32_bf16 v[24:27], v[164:167], v[210:213], v[24:27]
	v_mfma_f32_16x16x32_bf16 v[24:27], v[168:171], v[240:243], v[24:27]
	v_mfma_f32_16x16x32_bf16 v[16:19], v[172:175], v[210:213], v[16:19]
	v_mfma_f32_16x16x32_bf16 v[16:19], v[176:179], v[240:243], v[16:19]
	v_mfma_f32_16x16x32_bf16 v[8:11], v[164:167], v[244:247], v[8:11]
	v_mfma_f32_16x16x32_bf16 v[8:11], v[168:171], v[248:251], v[8:11]
	v_mfma_f32_16x16x32_bf16 v[4:7], v[172:175], v[244:247], v[4:7]
	v_mfma_f32_16x16x32_bf16 v[4:7], v[176:179], v[248:251], v[4:7]
	s_barrier
	s_add_i32 s57, 0, 0x18000
	v_add_u32_e32 v142, s57, v143
	s_add_i32 s58, 0, 0x1c000
	ds_read_b128 v[146:149], v142
	ds_read_b128 v[152:155], v142 offset:1024
	ds_read_b128 v[156:159], v142 offset:2048
	ds_read_b128 v[160:163], v142 offset:3072
	v_add_u32_e32 v142, s58, v143
	ds_read_b128 v[164:167], v142
	ds_read_b128 v[168:171], v142 offset:1024
	ds_read_b128 v[172:175], v142 offset:2048
	ds_read_b128 v[176:179], v142 offset:3072
	s_add_u32 s14, s14, 0x100000
	s_addc_u32 s15, s15, 0
	s_mov_b32 m0, s29
	v_lshl_add_u64 v[228:229], s[14:15], 0, v[136:137]
	ds_read_b128 v[180:183], v151 offset:32768
	ds_read_b128 v[184:187], v151 offset:33792
	ds_read_b128 v[188:191], v151 offset:34816
	ds_read_b128 v[206:209], v151 offset:35840
	ds_read_b128 v[210:213], v151 offset:36864
	ds_read_b128 v[240:243], v151 offset:37888
	ds_read_b128 v[244:247], v151 offset:38912
	ds_read_b128 v[248:251], v151 offset:39936
	global_load_lds_dwordx4 v[228:229], off
	v_lshl_add_u64 v[228:229], s[14:15], 0, v[134:135]
	s_mov_b32 m0, s30
	s_nop 0
	global_load_lds_dwordx4 v[228:229], off
	s_waitcnt vmcnt(8)
	s_waitcnt lgkmcnt(0)
	s_barrier
	s_waitcnt lgkmcnt(0)
	v_mfma_f32_16x16x32_bf16 v[128:131], v[146:149], v[180:183], v[128:131]
	v_mfma_f32_16x16x32_bf16 v[128:131], v[152:155], v[184:187], v[128:131]
	v_mfma_f32_16x16x32_bf16 v[124:127], v[156:159], v[180:183], v[124:127]
	v_mfma_f32_16x16x32_bf16 v[124:127], v[160:163], v[184:187], v[124:127]
	v_mfma_f32_16x16x32_bf16 v[112:115], v[146:149], v[188:191], v[112:115]
	v_mfma_f32_16x16x32_bf16 v[112:115], v[152:155], v[206:209], v[112:115]
	v_mfma_f32_16x16x32_bf16 v[108:111], v[156:159], v[188:191], v[108:111]
	v_mfma_f32_16x16x32_bf16 v[108:111], v[160:163], v[206:209], v[108:111]
	v_mfma_f32_16x16x32_bf16 v[96:99], v[146:149], v[210:213], v[96:99]
	v_mfma_f32_16x16x32_bf16 v[96:99], v[152:155], v[240:243], v[96:99]
	v_mfma_f32_16x16x32_bf16 v[92:95], v[156:159], v[210:213], v[92:95]
	v_mfma_f32_16x16x32_bf16 v[92:95], v[160:163], v[240:243], v[92:95]
	v_mfma_f32_16x16x32_bf16 v[80:83], v[146:149], v[244:247], v[80:83]
	v_mfma_f32_16x16x32_bf16 v[80:83], v[152:155], v[248:251], v[80:83]
	v_mfma_f32_16x16x32_bf16 v[76:79], v[156:159], v[244:247], v[76:79]
	v_mfma_f32_16x16x32_bf16 v[76:79], v[160:163], v[248:251], v[76:79]
	v_mfma_f32_16x16x32_bf16 v[120:123], v[164:167], v[180:183], v[120:123]
	v_mfma_f32_16x16x32_bf16 v[120:123], v[168:171], v[184:187], v[120:123]
	v_mfma_f32_16x16x32_bf16 v[116:119], v[172:175], v[180:183], v[116:119]
	v_mfma_f32_16x16x32_bf16 v[116:119], v[176:179], v[184:187], v[116:119]
	v_mfma_f32_16x16x32_bf16 v[104:107], v[164:167], v[188:191], v[104:107]
	v_mfma_f32_16x16x32_bf16 v[104:107], v[168:171], v[206:209], v[104:107]
	v_mfma_f32_16x16x32_bf16 v[100:103], v[172:175], v[188:191], v[100:103]
	v_mfma_f32_16x16x32_bf16 v[100:103], v[176:179], v[206:209], v[100:103]
	v_mfma_f32_16x16x32_bf16 v[88:91], v[164:167], v[210:213], v[88:91]
	v_mfma_f32_16x16x32_bf16 v[88:91], v[168:171], v[240:243], v[88:91]
	v_mfma_f32_16x16x32_bf16 v[84:87], v[172:175], v[210:213], v[84:87]
	v_mfma_f32_16x16x32_bf16 v[84:87], v[176:179], v[240:243], v[84:87]
	v_mfma_f32_16x16x32_bf16 v[72:75], v[164:167], v[244:247], v[72:75]
	v_mfma_f32_16x16x32_bf16 v[72:75], v[168:171], v[248:251], v[72:75]
	v_mfma_f32_16x16x32_bf16 v[68:71], v[172:175], v[244:247], v[68:71]
	v_mfma_f32_16x16x32_bf16 v[68:71], v[176:179], v[248:251], v[68:71]
	s_barrier
	s_add_i32 s14, s57, s26
	v_lshl_add_u64 v[192:193], v[192:193], 0, s[4:5]
	s_mov_b32 m0, s14
	ds_read_b128 v[180:183], v151 offset:49152
	ds_read_b128 v[184:187], v151 offset:50176
	ds_read_b128 v[188:191], v151 offset:51200
	ds_read_b128 v[206:209], v151 offset:52224
	ds_read_b128 v[210:213], v151 offset:53248
	ds_read_b128 v[240:243], v151 offset:54272
	ds_read_b128 v[244:247], v151 offset:55296
	ds_read_b128 v[248:251], v151 offset:56320
	global_load_lds_dwordx4 v[192:193], off
	s_add_i32 m0, s14, 0x2000
	s_add_u32 s12, s12, 0x100080
	v_lshl_add_u64 v[192:193], v[214:215], 0, s[4:5]
	s_addc_u32 s13, s13, 0
	s_add_i32 s14, s58, s26
	global_load_lds_dwordx4 v[192:193], off
	v_lshl_add_u64 v[192:193], s[12:13], 0, v[2:3]
	s_mov_b32 m0, s14
	s_nop 0
	global_load_lds_dwordx4 v[192:193], off
	v_lshl_add_u64 v[192:193], s[12:13], 0, v[132:133]
	s_add_i32 m0, s14, 0x2000
	s_nop 0
	global_load_lds_dwordx4 v[192:193], off
	v_lshl_add_u64 v[192:193], v[224:225], 0, s[4:5]
	s_mov_b32 m0, s31
	s_nop 0
	global_load_lds_dwordx4 v[192:193], off
	v_lshl_add_u64 v[192:193], v[226:227], 0, s[4:5]
	s_mov_b32 m0, s34
	s_nop 0
	global_load_lds_dwordx4 v[192:193], off
	s_waitcnt vmcnt(8)
	s_waitcnt lgkmcnt(0)
	s_barrier
	s_waitcnt lgkmcnt(0)
	v_mfma_f32_16x16x32_bf16 v[64:67], v[146:149], v[180:183], v[64:67]
	v_mfma_f32_16x16x32_bf16 v[64:67], v[152:155], v[184:187], v[64:67]
	v_mfma_f32_16x16x32_bf16 v[60:63], v[156:159], v[180:183], v[60:63]
	v_mfma_f32_16x16x32_bf16 v[60:63], v[160:163], v[184:187], v[60:63]
	v_mfma_f32_16x16x32_bf16 v[52:55], v[146:149], v[188:191], v[52:55]
	v_mfma_f32_16x16x32_bf16 v[52:55], v[152:155], v[206:209], v[52:55]
	v_mfma_f32_16x16x32_bf16 v[44:47], v[156:159], v[188:191], v[44:47]
	v_mfma_f32_16x16x32_bf16 v[44:47], v[160:163], v[206:209], v[44:47]
	v_mfma_f32_16x16x32_bf16 v[36:39], v[146:149], v[210:213], v[36:39]
	v_mfma_f32_16x16x32_bf16 v[36:39], v[152:155], v[240:243], v[36:39]
	v_mfma_f32_16x16x32_bf16 v[28:31], v[156:159], v[210:213], v[28:31]
	v_mfma_f32_16x16x32_bf16 v[28:31], v[160:163], v[240:243], v[28:31]
	v_mfma_f32_16x16x32_bf16 v[20:23], v[146:149], v[244:247], v[20:23]
	v_mfma_f32_16x16x32_bf16 v[20:23], v[152:155], v[248:251], v[20:23]
	v_mfma_f32_16x16x32_bf16 v[12:15], v[156:159], v[244:247], v[12:15]
	v_mfma_f32_16x16x32_bf16 v[12:15], v[160:163], v[248:251], v[12:15]
	v_mfma_f32_16x16x32_bf16 v[56:59], v[164:167], v[180:183], v[56:59]
	v_mfma_f32_16x16x32_bf16 v[56:59], v[168:171], v[184:187], v[56:59]
	v_mfma_f32_16x16x32_bf16 v[48:51], v[172:175], v[180:183], v[48:51]
	v_mfma_f32_16x16x32_bf16 v[48:51], v[176:179], v[184:187], v[48:51]
	v_mfma_f32_16x16x32_bf16 v[40:43], v[164:167], v[188:191], v[40:43]
	v_mfma_f32_16x16x32_bf16 v[40:43], v[168:171], v[206:209], v[40:43]
	v_mfma_f32_16x16x32_bf16 v[32:35], v[172:175], v[188:191], v[32:35]
	v_mfma_f32_16x16x32_bf16 v[32:35], v[176:179], v[206:209], v[32:35]
	v_mfma_f32_16x16x32_bf16 v[24:27], v[164:167], v[210:213], v[24:27]
	v_mfma_f32_16x16x32_bf16 v[24:27], v[168:171], v[240:243], v[24:27]
	v_mfma_f32_16x16x32_bf16 v[16:19], v[172:175], v[210:213], v[16:19]
	v_mfma_f32_16x16x32_bf16 v[16:19], v[176:179], v[240:243], v[16:19]
	v_mfma_f32_16x16x32_bf16 v[8:11], v[164:167], v[244:247], v[8:11]
	v_mfma_f32_16x16x32_bf16 v[8:11], v[168:171], v[248:251], v[8:11]
	v_mfma_f32_16x16x32_bf16 v[4:7], v[172:175], v[244:247], v[4:7]
	v_mfma_f32_16x16x32_bf16 v[4:7], v[176:179], v[248:251], v[4:7]
	s_barrier
	s_add_i32 s56, s56, 2
	s_add_u32 s52, s52, 0x100
	s_addc_u32 s53, s53, 0
	s_add_u32 s54, s54, 0x100
	s_addc_u32 s55, s55, 0
	s_cmp_gt_u32 s56, 61
	s_cbranch_scc0 .LBB0_127
	s_and_b64 vcc, exec, s[42:43]
	s_cbranch_vccz .LBB0_130
	s_barrier

.LBB0_1012:
	s_ashr_i32 s55, s54, 31
	s_lshl_b64 s[18:19], s[54:55], 21
	s_add_u32 s56, s26, s18
	s_addc_u32 s57, s27, s19
	s_and_b64 s[18:19], s[42:43], exec
	s_cselect_b32 s3, s57, s61
	s_cselect_b32 s28, s56, s60
	s_ashr_i32 s53, s52, 31
	s_lshl_b64 s[18:19], s[52:53], 21
	s_add_u32 s58, s30, s18
	s_addc_u32 s59, s31, s19
	s_and_b64 s[18:19], s[42:43], exec
	s_cselect_b32 s29, s59, s15
	s_cselect_b32 s53, s58, s14
	s_add_u32 s55, s14, 0x100
	v_mov_b32_e32 v4, 0
	s_addc_u32 s68, s15, 0
	s_mov_b32 s69, -2
	s_waitcnt lgkmcnt(0)
	v_mov_b32_e32 v5, v4
	v_mov_b64_e32 v[6:7], v[4:5]
	v_mov_b64_e32 v[8:9], v[4:5]
	v_mov_b64_e32 v[10:11], v[4:5]
	v_mov_b64_e32 v[12:13], v[4:5]
	v_mov_b64_e32 v[14:15], v[4:5]
	v_mov_b64_e32 v[16:17], v[4:5]
	v_mov_b64_e32 v[18:19], v[4:5]
	v_mov_b64_e32 v[20:21], v[4:5]
	v_mov_b64_e32 v[22:23], v[4:5]
	v_mov_b64_e32 v[24:25], v[4:5]
	v_mov_b64_e32 v[26:27], v[4:5]
	v_mov_b64_e32 v[28:29], v[4:5]
	v_mov_b64_e32 v[30:31], v[4:5]
	v_mov_b64_e32 v[32:33], v[4:5]
	v_mov_b64_e32 v[34:35], v[4:5]
	v_mov_b64_e32 v[36:37], v[4:5]
	v_mov_b64_e32 v[38:39], v[4:5]
	v_mov_b64_e32 v[40:41], v[4:5]
	v_mov_b64_e32 v[42:43], v[4:5]
	v_mov_b64_e32 v[44:45], v[4:5]
	v_mov_b64_e32 v[46:47], v[4:5]
	v_mov_b64_e32 v[52:53], v[4:5]
	v_mov_b64_e32 v[54:55], v[4:5]
	v_mov_b64_e32 v[68:69], v[4:5]
	v_mov_b64_e32 v[70:71], v[4:5]
	v_mov_b64_e32 v[72:73], v[4:5]
	v_mov_b64_e32 v[74:75], v[4:5]
	v_mov_b64_e32 v[76:77], v[4:5]
	v_mov_b64_e32 v[78:79], v[4:5]
	v_mov_b64_e32 v[80:81], v[4:5]
	v_mov_b64_e32 v[82:83], v[4:5]
	v_mov_b64_e32 v[84:85], v[4:5]
	v_mov_b64_e32 v[86:87], v[4:5]
	v_mov_b64_e32 v[88:89], v[4:5]
	v_mov_b64_e32 v[90:91], v[4:5]
	v_mov_b64_e32 v[92:93], v[4:5]
	v_mov_b64_e32 v[94:95], v[4:5]
	v_mov_b64_e32 v[96:97], v[4:5]
	v_mov_b64_e32 v[98:99], v[4:5]
	v_mov_b64_e32 v[100:101], v[4:5]
	v_mov_b64_e32 v[102:103], v[4:5]
	v_mov_b64_e32 v[104:105], v[4:5]
	v_mov_b64_e32 v[106:107], v[4:5]
	v_mov_b64_e32 v[108:109], v[4:5]
	v_mov_b64_e32 v[110:111], v[4:5]
	v_mov_b64_e32 v[112:113], v[4:5]
	v_mov_b64_e32 v[114:115], v[4:5]
	v_mov_b64_e32 v[116:117], v[4:5]
	v_mov_b64_e32 v[118:119], v[4:5]
	v_mov_b64_e32 v[120:121], v[4:5]
	v_mov_b64_e32 v[122:123], v[4:5]
	v_mov_b64_e32 v[124:125], v[4:5]
	v_mov_b64_e32 v[126:127], v[4:5]
	v_mov_b64_e32 v[128:129], v[4:5]
	v_mov_b64_e32 v[130:131], v[4:5]
	v_mov_b64_e32 v[132:133], v[4:5]
	v_mov_b64_e32 v[134:135], v[4:5]
	v_mov_b64_e32 v[136:137], v[4:5]
	v_mov_b64_e32 v[138:139], v[4:5]
	v_mov_b64_e32 v[140:141], v[4:5]
	v_mov_b64_e32 v[142:143], v[4:5]
	v_mov_b64_e32 v[144:145], v[4:5]
	v_mov_b64_e32 v[146:147], v[4:5]
.LBB0_1013:
	s_add_u32 s14, s60, 0x100
	s_addc_u32 s15, s61, 0
	s_add_i32 s70, 0, 0x10000
	s_cmp_eq_u32 s69, 60
	s_cselect_b32 s25, s3, s15
	s_cselect_b32 s24, s28, s14
	s_cselect_b32 s19, s29, s68
	s_cselect_b32 s18, s53, s55
	s_add_i32 s71, 0, 0x14000
	v_add_u32_e32 v64, s70, v178
	v_add_u32_e32 v160, s71, v178
	ds_read_b128 v[48:51], v64
	ds_read_b128 v[56:59], v64 offset:1024
	ds_read_b128 v[60:63], v64 offset:2048
	ds_read_b128 v[64:67], v64 offset:3072
	ds_read_b128 v[148:151], v160
	ds_read_b128 v[152:155], v160 offset:1024
	ds_read_b128 v[156:159], v160 offset:2048
	ds_read_b128 v[160:163], v160 offset:3072
	v_lshl_add_u64 v[214:215], s[60:61], 0, v[166:167]
	s_add_i32 m0, s36, 0xc000
	ds_read_b128 v[170:173], v180
	ds_read_b128 v[174:177], v180 offset:1024
	ds_read_b128 v[182:185], v180 offset:2048
	ds_read_b128 v[186:189], v180 offset:3072
	ds_read_b128 v[190:193], v180 offset:4096
	ds_read_b128 v[206:209], v180 offset:5120
	ds_read_b128 v[210:213], v180 offset:6144
	ds_read_b128 v[224:227], v180 offset:7168
	global_load_lds_dwordx4 v[214:215], off
	v_lshl_add_u64 v[214:215], s[60:61], 0, v[168:169]
	s_add_i32 m0, s36, 0xe000
	s_nop 0
	global_load_lds_dwordx4 v[214:215], off
	s_waitcnt vmcnt(8)
	s_waitcnt lgkmcnt(0)
	s_barrier
	s_waitcnt lgkmcnt(0)
	v_mfma_f32_16x16x32_bf16 v[144:147], v[48:51], v[170:173], v[144:147]
	v_mfma_f32_16x16x32_bf16 v[144:147], v[56:59], v[174:177], v[144:147]
	v_mfma_f32_16x16x32_bf16 v[140:143], v[60:63], v[170:173], v[140:143]
	v_mfma_f32_16x16x32_bf16 v[140:143], v[64:67], v[174:177], v[140:143]
	v_mfma_f32_16x16x32_bf16 v[128:131], v[48:51], v[182:185], v[128:131]
	v_mfma_f32_16x16x32_bf16 v[128:131], v[56:59], v[186:189], v[128:131]
	v_mfma_f32_16x16x32_bf16 v[124:127], v[60:63], v[182:185], v[124:127]
	v_mfma_f32_16x16x32_bf16 v[124:127], v[64:67], v[186:189], v[124:127]
	v_mfma_f32_16x16x32_bf16 v[112:115], v[48:51], v[190:193], v[112:115]
	v_mfma_f32_16x16x32_bf16 v[112:115], v[56:59], v[206:209], v[112:115]
	v_mfma_f32_16x16x32_bf16 v[108:111], v[60:63], v[190:193], v[108:111]
	v_mfma_f32_16x16x32_bf16 v[108:111], v[64:67], v[206:209], v[108:111]
	v_mfma_f32_16x16x32_bf16 v[96:99], v[48:51], v[210:213], v[96:99]
	v_mfma_f32_16x16x32_bf16 v[96:99], v[56:59], v[224:227], v[96:99]
	v_mfma_f32_16x16x32_bf16 v[92:95], v[60:63], v[210:213], v[92:95]
	v_mfma_f32_16x16x32_bf16 v[92:95], v[64:67], v[224:227], v[92:95]
	v_mfma_f32_16x16x32_bf16 v[136:139], v[148:151], v[170:173], v[136:139]
	v_mfma_f32_16x16x32_bf16 v[136:139], v[152:155], v[174:177], v[136:139]
	v_mfma_f32_16x16x32_bf16 v[132:135], v[156:159], v[170:173], v[132:135]
	v_mfma_f32_16x16x32_bf16 v[132:135], v[160:163], v[174:177], v[132:135]
	v_mfma_f32_16x16x32_bf16 v[120:123], v[148:151], v[182:185], v[120:123]
	v_mfma_f32_16x16x32_bf16 v[120:123], v[152:155], v[186:189], v[120:123]
	v_mfma_f32_16x16x32_bf16 v[116:119], v[156:159], v[182:185], v[116:119]
	v_mfma_f32_16x16x32_bf16 v[116:119], v[160:163], v[186:189], v[116:119]
	v_mfma_f32_16x16x32_bf16 v[104:107], v[148:151], v[190:193], v[104:107]
	v_mfma_f32_16x16x32_bf16 v[104:107], v[152:155], v[206:209], v[104:107]
	v_mfma_f32_16x16x32_bf16 v[100:103], v[156:159], v[190:193], v[100:103]
	v_mfma_f32_16x16x32_bf16 v[100:103], v[160:163], v[206:209], v[100:103]
	v_mfma_f32_16x16x32_bf16 v[88:91], v[148:151], v[210:213], v[88:91]
	v_mfma_f32_16x16x32_bf16 v[88:91], v[152:155], v[224:227], v[88:91]
	v_mfma_f32_16x16x32_bf16 v[84:87], v[156:159], v[210:213], v[84:87]
	v_mfma_f32_16x16x32_bf16 v[84:87], v[160:163], v[224:227], v[84:87]
	s_barrier
	s_add_i32 s60, s70, s35
	v_lshl_add_u64 v[214:215], s[18:19], 0, v[2:3]
	s_mov_b32 m0, s60
	ds_read_b128 v[170:173], v180 offset:16384
	ds_read_b128 v[174:177], v180 offset:17408
	ds_read_b128 v[182:185], v180 offset:18432
	ds_read_b128 v[186:189], v180 offset:19456
	ds_read_b128 v[190:193], v180 offset:20480
	ds_read_b128 v[206:209], v180 offset:21504
	ds_read_b128 v[210:213], v180 offset:22528
	ds_read_b128 v[224:227], v180 offset:23552
	global_load_lds_dwordx4 v[214:215], off
	s_add_i32 m0, s60, 0x2000
	s_add_u32 s60, s18, 0x100000
	v_lshl_add_u64 v[228:229], s[18:19], 0, v[164:165]
	s_addc_u32 s61, s19, 0
	s_add_i32 s70, s71, s35
	global_load_lds_dwordx4 v[228:229], off
	v_lshl_add_u64 v[230:231], s[60:61], 0, v[2:3]
	s_mov_b32 m0, s70
	v_lshl_add_u64 v[240:241], s[24:25], 0, v[164:165]
	global_load_lds_dwordx4 v[230:231], off
	v_lshl_add_u64 v[230:231], s[60:61], 0, v[164:165]
	s_add_i32 m0, s70, 0x2000
	s_nop 0
	global_load_lds_dwordx4 v[230:231], off
	v_lshl_add_u64 v[230:231], s[24:25], 0, v[2:3]
	s_mov_b32 m0, s36
	s_nop 0
	global_load_lds_dwordx4 v[230:231], off
	s_mov_b32 m0, s37
	s_nop 0
	global_load_lds_dwordx4 v[240:241], off
	s_waitcnt vmcnt(8)
	s_waitcnt lgkmcnt(0)
	s_barrier
	s_waitcnt lgkmcnt(0)
	v_mfma_f32_16x16x32_bf16 v[80:83], v[48:51], v[170:173], v[80:83]
	v_mfma_f32_16x16x32_bf16 v[80:83], v[56:59], v[174:177], v[80:83]
	v_mfma_f32_16x16x32_bf16 v[76:79], v[60:63], v[170:173], v[76:79]
	v_mfma_f32_16x16x32_bf16 v[76:79], v[64:67], v[174:177], v[76:79]
	v_mfma_f32_16x16x32_bf16 v[52:55], v[48:51], v[182:185], v[52:55]
	v_mfma_f32_16x16x32_bf16 v[52:55], v[56:59], v[186:189], v[52:55]
	v_mfma_f32_16x16x32_bf16 v[44:47], v[60:63], v[182:185], v[44:47]
	v_mfma_f32_16x16x32_bf16 v[44:47], v[64:67], v[186:189], v[44:47]
	v_mfma_f32_16x16x32_bf16 v[32:35], v[48:51], v[190:193], v[32:35]
	v_mfma_f32_16x16x32_bf16 v[32:35], v[56:59], v[206:209], v[32:35]
	v_mfma_f32_16x16x32_bf16 v[28:31], v[60:63], v[190:193], v[28:31]
	v_mfma_f32_16x16x32_bf16 v[28:31], v[64:67], v[206:209], v[28:31]
	v_mfma_f32_16x16x32_bf16 v[16:19], v[48:51], v[210:213], v[16:19]
	v_mfma_f32_16x16x32_bf16 v[16:19], v[56:59], v[224:227], v[16:19]
	v_mfma_f32_16x16x32_bf16 v[12:15], v[60:63], v[210:213], v[12:15]
	v_mfma_f32_16x16x32_bf16 v[12:15], v[64:67], v[224:227], v[12:15]
	v_mfma_f32_16x16x32_bf16 v[40:43], v[148:151], v[182:185], v[40:43]
	v_mfma_f32_16x16x32_bf16 v[40:43], v[152:155], v[186:189], v[40:43]
	v_mfma_f32_16x16x32_bf16 v[36:39], v[156:159], v[182:185], v[36:39]
	v_mfma_f32_16x16x32_bf16 v[36:39], v[160:163], v[186:189], v[36:39]
	v_mfma_f32_16x16x32_bf16 v[24:27], v[148:151], v[190:193], v[24:27]
	v_mfma_f32_16x16x32_bf16 v[24:27], v[152:155], v[206:209], v[24:27]
	v_mfma_f32_16x16x32_bf16 v[20:23], v[156:159], v[190:193], v[20:23]
	v_mfma_f32_16x16x32_bf16 v[20:23], v[160:163], v[206:209], v[20:23]
	v_mfma_f32_16x16x32_bf16 v[8:11], v[148:151], v[210:213], v[8:11]
	v_mfma_f32_16x16x32_bf16 v[8:11], v[152:155], v[224:227], v[8:11]
	v_mfma_f32_16x16x32_bf16 v[4:7], v[156:159], v[210:213], v[4:7]
	v_mfma_f32_16x16x32_bf16 v[4:7], v[160:163], v[224:227], v[4:7]
	v_mfma_f32_16x16x32_bf16 v[48:51], v[148:151], v[170:173], v[72:75]
	v_mfma_f32_16x16x32_bf16 v[48:51], v[152:155], v[174:177], v[48:51]
	v_mfma_f32_16x16x32_bf16 v[56:59], v[156:159], v[170:173], v[68:71]
	v_mfma_f32_16x16x32_bf16 v[56:59], v[160:163], v[174:177], v[56:59]
	s_barrier
	s_add_i32 s60, 0, 0x18000
	s_add_i32 s61, 0, 0x1c000
	v_add_u32_e32 v72, s60, v178
	v_add_u32_e32 v160, s61, v178
	ds_read_b128 v[60:63], v72
	ds_read_b128 v[64:67], v72 offset:1024
	ds_read_b128 v[68:71], v72 offset:2048
	ds_read_b128 v[72:75], v72 offset:3072
	ds_read_b128 v[148:151], v160
	ds_read_b128 v[152:155], v160 offset:1024
	ds_read_b128 v[156:159], v160 offset:2048
	ds_read_b128 v[160:163], v160 offset:3072
	s_add_u32 s24, s24, 0x100000
	s_addc_u32 s25, s25, 0
	s_mov_b32 m0, s62
	v_lshl_add_u64 v[242:243], s[24:25], 0, v[2:3]
	ds_read_b128 v[170:173], v180 offset:32768
	ds_read_b128 v[174:177], v180 offset:33792
	ds_read_b128 v[182:185], v180 offset:34816
	ds_read_b128 v[186:189], v180 offset:35840
	ds_read_b128 v[190:193], v180 offset:36864
	ds_read_b128 v[206:209], v180 offset:37888
	ds_read_b128 v[210:213], v180 offset:38912
	ds_read_b128 v[224:227], v180 offset:39936
	global_load_lds_dwordx4 v[242:243], off
	v_lshl_add_u64 v[242:243], s[24:25], 0, v[164:165]
	s_mov_b32 m0, s63
	s_nop 0
	global_load_lds_dwordx4 v[242:243], off
	s_waitcnt vmcnt(8)
	s_waitcnt lgkmcnt(0)
	s_barrier
	s_waitcnt lgkmcnt(0)
	v_mfma_f32_16x16x32_bf16 v[144:147], v[60:63], v[170:173], v[144:147]
	v_mfma_f32_16x16x32_bf16 v[144:147], v[64:67], v[174:177], v[144:147]
	v_mfma_f32_16x16x32_bf16 v[140:143], v[68:71], v[170:173], v[140:143]
	v_mfma_f32_16x16x32_bf16 v[140:143], v[72:75], v[174:177], v[140:143]
	v_mfma_f32_16x16x32_bf16 v[128:131], v[60:63], v[182:185], v[128:131]
	v_mfma_f32_16x16x32_bf16 v[128:131], v[64:67], v[186:189], v[128:131]
	v_mfma_f32_16x16x32_bf16 v[124:127], v[68:71], v[182:185], v[124:127]
	v_mfma_f32_16x16x32_bf16 v[124:127], v[72:75], v[186:189], v[124:127]
	v_mfma_f32_16x16x32_bf16 v[112:115], v[60:63], v[190:193], v[112:115]
	v_mfma_f32_16x16x32_bf16 v[112:115], v[64:67], v[206:209], v[112:115]
	v_mfma_f32_16x16x32_bf16 v[108:111], v[68:71], v[190:193], v[108:111]
	v_mfma_f32_16x16x32_bf16 v[108:111], v[72:75], v[206:209], v[108:111]
	v_mfma_f32_16x16x32_bf16 v[96:99], v[60:63], v[210:213], v[96:99]
	v_mfma_f32_16x16x32_bf16 v[96:99], v[64:67], v[224:227], v[96:99]
	v_mfma_f32_16x16x32_bf16 v[92:95], v[68:71], v[210:213], v[92:95]
	v_mfma_f32_16x16x32_bf16 v[92:95], v[72:75], v[224:227], v[92:95]
	v_mfma_f32_16x16x32_bf16 v[136:139], v[148:151], v[170:173], v[136:139]
	v_mfma_f32_16x16x32_bf16 v[136:139], v[152:155], v[174:177], v[136:139]
	v_mfma_f32_16x16x32_bf16 v[132:135], v[156:159], v[170:173], v[132:135]
	v_mfma_f32_16x16x32_bf16 v[132:135], v[160:163], v[174:177], v[132:135]
	v_mfma_f32_16x16x32_bf16 v[120:123], v[148:151], v[182:185], v[120:123]
	v_mfma_f32_16x16x32_bf16 v[120:123], v[152:155], v[186:189], v[120:123]
	v_mfma_f32_16x16x32_bf16 v[116:119], v[156:159], v[182:185], v[116:119]
	v_mfma_f32_16x16x32_bf16 v[116:119], v[160:163], v[186:189], v[116:119]
	v_mfma_f32_16x16x32_bf16 v[104:107], v[148:151], v[190:193], v[104:107]
	v_mfma_f32_16x16x32_bf16 v[104:107], v[152:155], v[206:209], v[104:107]
	v_mfma_f32_16x16x32_bf16 v[100:103], v[156:159], v[190:193], v[100:103]
	v_mfma_f32_16x16x32_bf16 v[100:103], v[160:163], v[206:209], v[100:103]
	v_mfma_f32_16x16x32_bf16 v[88:91], v[148:151], v[210:213], v[88:91]
	v_mfma_f32_16x16x32_bf16 v[88:91], v[152:155], v[224:227], v[88:91]
	v_mfma_f32_16x16x32_bf16 v[84:87], v[156:159], v[210:213], v[84:87]
	v_mfma_f32_16x16x32_bf16 v[84:87], v[160:163], v[224:227], v[84:87]
	s_barrier
	s_add_i32 s24, s60, s35
	v_lshl_add_u64 v[214:215], v[214:215], 0, s[4:5]
	s_mov_b32 m0, s24
	ds_read_b128 v[170:173], v180 offset:49152
	ds_read_b128 v[174:177], v180 offset:50176
	ds_read_b128 v[182:185], v180 offset:51200
	ds_read_b128 v[186:189], v180 offset:52224
	ds_read_b128 v[190:193], v180 offset:53248
	ds_read_b128 v[206:209], v180 offset:54272
	ds_read_b128 v[210:213], v180 offset:55296
	ds_read_b128 v[224:227], v180 offset:56320
	global_load_lds_dwordx4 v[214:215], off
	s_add_i32 m0, s24, 0x2000
	s_add_u32 s18, s18, 0x100080
	v_lshl_add_u64 v[214:215], v[228:229], 0, s[4:5]
	s_addc_u32 s19, s19, 0
	s_add_i32 s24, s61, s35
	global_load_lds_dwordx4 v[214:215], off
	v_lshl_add_u64 v[214:215], s[18:19], 0, v[2:3]
	s_mov_b32 m0, s24
	s_nop 0
	global_load_lds_dwordx4 v[214:215], off
	v_lshl_add_u64 v[214:215], s[18:19], 0, v[164:165]
	s_add_i32 m0, s24, 0x2000
	s_nop 0
	global_load_lds_dwordx4 v[214:215], off
	v_lshl_add_u64 v[214:215], v[230:231], 0, s[4:5]
	s_mov_b32 m0, s65
	s_nop 0
	global_load_lds_dwordx4 v[214:215], off
	v_lshl_add_u64 v[214:215], v[240:241], 0, s[4:5]
	s_mov_b32 m0, s66
	s_nop 0
	global_load_lds_dwordx4 v[214:215], off
	s_waitcnt vmcnt(8)
	s_waitcnt lgkmcnt(0)
	s_barrier
	s_waitcnt lgkmcnt(0)
	v_mfma_f32_16x16x32_bf16 v[80:83], v[60:63], v[170:173], v[80:83]
	v_mfma_f32_16x16x32_bf16 v[76:79], v[68:71], v[170:173], v[76:79]
	v_mfma_f32_16x16x32_bf16 v[52:55], v[60:63], v[182:185], v[52:55]
	v_mfma_f32_16x16x32_bf16 v[44:47], v[68:71], v[182:185], v[44:47]
	v_mfma_f32_16x16x32_bf16 v[32:35], v[60:63], v[190:193], v[32:35]
	v_mfma_f32_16x16x32_bf16 v[28:31], v[68:71], v[190:193], v[28:31]
	v_mfma_f32_16x16x32_bf16 v[16:19], v[60:63], v[210:213], v[16:19]
	v_mfma_f32_16x16x32_bf16 v[12:15], v[68:71], v[210:213], v[12:15]
	v_mfma_f32_16x16x32_bf16 v[80:83], v[64:67], v[174:177], v[80:83]
	v_mfma_f32_16x16x32_bf16 v[76:79], v[72:75], v[174:177], v[76:79]
	v_mfma_f32_16x16x32_bf16 v[52:55], v[64:67], v[186:189], v[52:55]
	v_mfma_f32_16x16x32_bf16 v[44:47], v[72:75], v[186:189], v[44:47]
	v_mfma_f32_16x16x32_bf16 v[32:35], v[64:67], v[206:209], v[32:35]
	v_mfma_f32_16x16x32_bf16 v[28:31], v[72:75], v[206:209], v[28:31]
	v_mfma_f32_16x16x32_bf16 v[16:19], v[64:67], v[224:227], v[16:19]
	v_mfma_f32_16x16x32_bf16 v[12:15], v[72:75], v[224:227], v[12:15]
	v_mfma_f32_16x16x32_bf16 v[48:51], v[148:151], v[170:173], v[48:51]
	v_mfma_f32_16x16x32_bf16 v[72:75], v[152:155], v[174:177], v[48:51]
	v_mfma_f32_16x16x32_bf16 v[48:51], v[156:159], v[170:173], v[56:59]
	v_mfma_f32_16x16x32_bf16 v[40:43], v[148:151], v[182:185], v[40:43]
	v_mfma_f32_16x16x32_bf16 v[36:39], v[156:159], v[182:185], v[36:39]
	v_mfma_f32_16x16x32_bf16 v[24:27], v[148:151], v[190:193], v[24:27]
	v_mfma_f32_16x16x32_bf16 v[20:23], v[156:159], v[190:193], v[20:23]
	v_mfma_f32_16x16x32_bf16 v[8:11], v[148:151], v[210:213], v[8:11]
	v_mfma_f32_16x16x32_bf16 v[4:7], v[156:159], v[210:213], v[4:7]
	v_mfma_f32_16x16x32_bf16 v[68:71], v[160:163], v[174:177], v[48:51]
	v_mfma_f32_16x16x32_bf16 v[40:43], v[152:155], v[186:189], v[40:43]
	v_mfma_f32_16x16x32_bf16 v[36:39], v[160:163], v[186:189], v[36:39]
	v_mfma_f32_16x16x32_bf16 v[24:27], v[152:155], v[206:209], v[24:27]
	v_mfma_f32_16x16x32_bf16 v[20:23], v[160:163], v[206:209], v[20:23]
	v_mfma_f32_16x16x32_bf16 v[8:11], v[152:155], v[224:227], v[8:11]
	v_mfma_f32_16x16x32_bf16 v[4:7], v[160:163], v[224:227], v[4:7]
	s_barrier
	s_add_i32 s69, s69, 2
	s_add_u32 s55, s55, 0x100
	s_addc_u32 s68, s68, 0
	s_cmp_gt_u32 s69, 61
	s_mov_b64 s[60:61], s[14:15]
	s_cbranch_scc0 .LBB0_1013
	s_and_b64 vcc, exec, s[50:51]
	s_cbranch_vccz .LBB0_1016
	s_barrier

.LBB0_1157:
	s_ashr_i32 s47, s46, 31
	s_lshl_b64 s[24:25], s[46:47], 21
	s_add_u32 s48, s26, s24
	s_addc_u32 s49, s27, s25
	s_and_b64 s[24:25], s[40:41], exec
	s_cselect_b32 s3, s49, s19
	s_cselect_b32 s24, s48, s18
	s_ashr_i32 s45, s44, 31
	s_lshl_b64 s[28:29], s[44:45], 21
	s_add_u32 s50, s30, s28
	s_addc_u32 s51, s31, s29
	s_and_b64 s[28:29], s[40:41], exec
	s_cselect_b32 s25, s51, s15
	s_cselect_b32 s28, s50, s14
	s_add_u32 s52, s18, 0x100080
	s_addc_u32 s53, s19, 0
	s_add_u32 s29, s14, 0x100
	v_mov_b32_e32 v4, 0
	s_addc_u32 s45, s15, 0
	s_mov_b32 s47, -2
	v_mov_b32_e32 v5, v4
	v_mov_b64_e32 v[6:7], v[4:5]
	v_mov_b64_e32 v[8:9], v[4:5]
	v_mov_b64_e32 v[10:11], v[4:5]
	v_mov_b64_e32 v[12:13], v[4:5]
	v_mov_b64_e32 v[14:15], v[4:5]
	v_mov_b64_e32 v[16:17], v[4:5]
	v_mov_b64_e32 v[18:19], v[4:5]
	v_mov_b64_e32 v[20:21], v[4:5]
	v_mov_b64_e32 v[22:23], v[4:5]
	v_mov_b64_e32 v[24:25], v[4:5]
	v_mov_b64_e32 v[26:27], v[4:5]
	v_mov_b64_e32 v[28:29], v[4:5]
	v_mov_b64_e32 v[30:31], v[4:5]
	v_mov_b64_e32 v[32:33], v[4:5]
	v_mov_b64_e32 v[34:35], v[4:5]
	v_mov_b64_e32 v[36:37], v[4:5]
	v_mov_b64_e32 v[38:39], v[4:5]
	v_mov_b64_e32 v[40:41], v[4:5]
	v_mov_b64_e32 v[42:43], v[4:5]
	v_mov_b64_e32 v[44:45], v[4:5]
	v_mov_b64_e32 v[46:47], v[4:5]
	v_mov_b64_e32 v[48:49], v[4:5]
	v_mov_b64_e32 v[50:51], v[4:5]
	v_mov_b64_e32 v[52:53], v[4:5]
	v_mov_b64_e32 v[54:55], v[4:5]
	v_mov_b64_e32 v[56:57], v[4:5]
	v_mov_b64_e32 v[58:59], v[4:5]
	v_mov_b64_e32 v[60:61], v[4:5]
	v_mov_b64_e32 v[62:63], v[4:5]
	v_mov_b64_e32 v[64:65], v[4:5]
	v_mov_b64_e32 v[66:67], v[4:5]
	v_mov_b64_e32 v[68:69], v[4:5]
	v_mov_b64_e32 v[70:71], v[4:5]
	v_mov_b64_e32 v[72:73], v[4:5]
	v_mov_b64_e32 v[74:75], v[4:5]
	v_mov_b64_e32 v[76:77], v[4:5]
	v_mov_b64_e32 v[78:79], v[4:5]
	v_mov_b64_e32 v[80:81], v[4:5]
	v_mov_b64_e32 v[82:83], v[4:5]
	v_mov_b64_e32 v[84:85], v[4:5]
	v_mov_b64_e32 v[86:87], v[4:5]
	v_mov_b64_e32 v[88:89], v[4:5]
	v_mov_b64_e32 v[90:91], v[4:5]
	v_mov_b64_e32 v[92:93], v[4:5]
	v_mov_b64_e32 v[94:95], v[4:5]
	v_mov_b64_e32 v[96:97], v[4:5]
	v_mov_b64_e32 v[98:99], v[4:5]
	v_mov_b64_e32 v[100:101], v[4:5]
	v_mov_b64_e32 v[102:103], v[4:5]
	v_mov_b64_e32 v[104:105], v[4:5]
	v_mov_b64_e32 v[106:107], v[4:5]
	v_mov_b64_e32 v[108:109], v[4:5]
	v_mov_b64_e32 v[110:111], v[4:5]
	v_mov_b64_e32 v[112:113], v[4:5]
	v_mov_b64_e32 v[114:115], v[4:5]
	v_mov_b64_e32 v[116:117], v[4:5]
	v_mov_b64_e32 v[118:119], v[4:5]
	v_mov_b64_e32 v[120:121], v[4:5]
	v_mov_b64_e32 v[122:123], v[4:5]
	v_mov_b64_e32 v[124:125], v[4:5]
	v_mov_b64_e32 v[126:127], v[4:5]
	v_mov_b64_e32 v[128:129], v[4:5]
	v_mov_b64_e32 v[130:131], v[4:5]
.LBB0_1158:
	s_add_u32 s14, s52, 0xfff00080
	s_addc_u32 s15, s53, -1
	s_add_i32 s59, 0, 0x10000
	s_cmp_eq_u32 s47, 60
	s_cselect_b32 s19, s3, s15
	s_cselect_b32 s18, s24, s14
	v_add_u32_e32 v142, s59, v143
	s_cselect_b32 s15, s25, s45
	s_cselect_b32 s14, s28, s29
	s_add_i32 s62, 0, 0x14000
	ds_read_b128 v[144:147], v142
	ds_read_b128 v[152:155], v142 offset:1024
	ds_read_b128 v[156:159], v142 offset:2048
	ds_read_b128 v[160:163], v142 offset:3072
	v_add_u32_e32 v142, s62, v143
	ds_read_b128 v[164:167], v142
	ds_read_b128 v[168:171], v142 offset:1024
	ds_read_b128 v[172:175], v142 offset:2048
	ds_read_b128 v[176:179], v142 offset:3072
	v_lshl_add_u64 v[192:193], s[52:53], 0, v[138:139]
	s_add_i32 m0, s36, 0xc000
	ds_read_b128 v[180:183], v151
	ds_read_b128 v[184:187], v151 offset:1024
	ds_read_b128 v[188:191], v151 offset:2048
	ds_read_b128 v[206:209], v151 offset:3072
	ds_read_b128 v[210:213], v151 offset:4096
	ds_read_b128 v[224:227], v151 offset:5120
	ds_read_b128 v[228:231], v151 offset:6144
	ds_read_b128 v[240:243], v151 offset:7168
	global_load_lds_dwordx4 v[192:193], off
	v_lshl_add_u64 v[192:193], s[52:53], 0, v[140:141]
	s_add_i32 m0, s36, 0xe000
	s_nop 0
	global_load_lds_dwordx4 v[192:193], off
	s_waitcnt vmcnt(8)
	s_waitcnt lgkmcnt(0)
	s_barrier
	s_waitcnt lgkmcnt(0)
	v_mfma_f32_16x16x32_bf16 v[128:131], v[144:147], v[180:183], v[128:131]
	v_mfma_f32_16x16x32_bf16 v[128:131], v[152:155], v[184:187], v[128:131]
	v_mfma_f32_16x16x32_bf16 v[124:127], v[156:159], v[180:183], v[124:127]
	v_mfma_f32_16x16x32_bf16 v[124:127], v[160:163], v[184:187], v[124:127]
	v_mfma_f32_16x16x32_bf16 v[112:115], v[144:147], v[188:191], v[112:115]
	v_mfma_f32_16x16x32_bf16 v[112:115], v[152:155], v[206:209], v[112:115]
	v_mfma_f32_16x16x32_bf16 v[108:111], v[156:159], v[188:191], v[108:111]
	v_mfma_f32_16x16x32_bf16 v[108:111], v[160:163], v[206:209], v[108:111]
	v_mfma_f32_16x16x32_bf16 v[96:99], v[144:147], v[210:213], v[96:99]
	v_mfma_f32_16x16x32_bf16 v[96:99], v[152:155], v[224:227], v[96:99]
	v_mfma_f32_16x16x32_bf16 v[92:95], v[156:159], v[210:213], v[92:95]
	v_mfma_f32_16x16x32_bf16 v[92:95], v[160:163], v[224:227], v[92:95]
	v_mfma_f32_16x16x32_bf16 v[80:83], v[144:147], v[228:231], v[80:83]
	v_mfma_f32_16x16x32_bf16 v[80:83], v[152:155], v[240:243], v[80:83]
	v_mfma_f32_16x16x32_bf16 v[76:79], v[156:159], v[228:231], v[76:79]
	v_mfma_f32_16x16x32_bf16 v[76:79], v[160:163], v[240:243], v[76:79]
	v_mfma_f32_16x16x32_bf16 v[120:123], v[164:167], v[180:183], v[120:123]
	v_mfma_f32_16x16x32_bf16 v[120:123], v[168:171], v[184:187], v[120:123]
	v_mfma_f32_16x16x32_bf16 v[116:119], v[172:175], v[180:183], v[116:119]
	v_mfma_f32_16x16x32_bf16 v[116:119], v[176:179], v[184:187], v[116:119]
	v_mfma_f32_16x16x32_bf16 v[104:107], v[164:167], v[188:191], v[104:107]
	v_mfma_f32_16x16x32_bf16 v[104:107], v[168:171], v[206:209], v[104:107]
	v_mfma_f32_16x16x32_bf16 v[100:103], v[172:175], v[188:191], v[100:103]
	v_mfma_f32_16x16x32_bf16 v[100:103], v[176:179], v[206:209], v[100:103]
	v_mfma_f32_16x16x32_bf16 v[88:91], v[164:167], v[210:213], v[88:91]
	v_mfma_f32_16x16x32_bf16 v[88:91], v[168:171], v[224:227], v[88:91]
	v_mfma_f32_16x16x32_bf16 v[84:87], v[172:175], v[210:213], v[84:87]
	v_mfma_f32_16x16x32_bf16 v[84:87], v[176:179], v[224:227], v[84:87]
	v_mfma_f32_16x16x32_bf16 v[72:75], v[164:167], v[228:231], v[72:75]
	v_mfma_f32_16x16x32_bf16 v[72:75], v[168:171], v[240:243], v[72:75]
	v_mfma_f32_16x16x32_bf16 v[68:71], v[172:175], v[228:231], v[68:71]
	v_mfma_f32_16x16x32_bf16 v[68:71], v[176:179], v[240:243], v[68:71]
	s_barrier
	s_add_i32 s59, s59, s35
	v_lshl_add_u64 v[192:193], s[14:15], 0, v[2:3]
	s_mov_b32 m0, s59
	ds_read_b128 v[180:183], v151 offset:16384
	ds_read_b128 v[184:187], v151 offset:17408
	ds_read_b128 v[188:191], v151 offset:18432
	ds_read_b128 v[206:209], v151 offset:19456
	ds_read_b128 v[210:213], v151 offset:20480
	ds_read_b128 v[224:227], v151 offset:21504
	ds_read_b128 v[228:231], v151 offset:22528
	ds_read_b128 v[240:243], v151 offset:23552
	global_load_lds_dwordx4 v[192:193], off
	s_add_i32 m0, s59, 0x2000
	s_add_u32 s60, s14, 0x100000
	v_lshl_add_u64 v[214:215], s[14:15], 0, v[132:133]
	s_addc_u32 s61, s15, 0
	s_add_i32 s59, s62, s35
	global_load_lds_dwordx4 v[214:215], off
	v_lshl_add_u64 v[244:245], s[60:61], 0, v[2:3]
	s_mov_b32 m0, s59
	v_lshl_add_u64 v[246:247], s[18:19], 0, v[134:135]
	global_load_lds_dwordx4 v[244:245], off
	v_lshl_add_u64 v[244:245], s[60:61], 0, v[132:133]
	s_add_i32 m0, s59, 0x2000
	s_nop 0
	global_load_lds_dwordx4 v[244:245], off
	v_lshl_add_u64 v[244:245], s[18:19], 0, v[136:137]
	s_mov_b32 m0, s36
	s_nop 0
	global_load_lds_dwordx4 v[244:245], off
	s_mov_b32 m0, s37
	s_nop 0
	global_load_lds_dwordx4 v[246:247], off
	s_waitcnt vmcnt(8)
	s_waitcnt lgkmcnt(0)
	s_barrier
	s_waitcnt lgkmcnt(0)
	v_mfma_f32_16x16x32_bf16 v[64:67], v[144:147], v[180:183], v[64:67]
	v_mfma_f32_16x16x32_bf16 v[64:67], v[152:155], v[184:187], v[64:67]
	v_mfma_f32_16x16x32_bf16 v[60:63], v[156:159], v[180:183], v[60:63]
	v_mfma_f32_16x16x32_bf16 v[60:63], v[160:163], v[184:187], v[60:63]
	v_mfma_f32_16x16x32_bf16 v[48:51], v[144:147], v[188:191], v[48:51]
	v_mfma_f32_16x16x32_bf16 v[48:51], v[152:155], v[206:209], v[48:51]
	v_mfma_f32_16x16x32_bf16 v[44:47], v[156:159], v[188:191], v[44:47]
	v_mfma_f32_16x16x32_bf16 v[44:47], v[160:163], v[206:209], v[44:47]
	v_mfma_f32_16x16x32_bf16 v[32:35], v[144:147], v[210:213], v[32:35]
	v_mfma_f32_16x16x32_bf16 v[32:35], v[152:155], v[224:227], v[32:35]
	v_mfma_f32_16x16x32_bf16 v[28:31], v[156:159], v[210:213], v[28:31]
	v_mfma_f32_16x16x32_bf16 v[28:31], v[160:163], v[224:227], v[28:31]
	v_mfma_f32_16x16x32_bf16 v[16:19], v[144:147], v[228:231], v[16:19]
	v_mfma_f32_16x16x32_bf16 v[16:19], v[152:155], v[240:243], v[16:19]
	v_mfma_f32_16x16x32_bf16 v[12:15], v[156:159], v[228:231], v[12:15]
	v_mfma_f32_16x16x32_bf16 v[12:15], v[160:163], v[240:243], v[12:15]
	v_mfma_f32_16x16x32_bf16 v[56:59], v[164:167], v[180:183], v[56:59]
	v_mfma_f32_16x16x32_bf16 v[56:59], v[168:171], v[184:187], v[56:59]
	v_mfma_f32_16x16x32_bf16 v[52:55], v[172:175], v[180:183], v[52:55]
	v_mfma_f32_16x16x32_bf16 v[52:55], v[176:179], v[184:187], v[52:55]
	v_mfma_f32_16x16x32_bf16 v[40:43], v[164:167], v[188:191], v[40:43]
	v_mfma_f32_16x16x32_bf16 v[40:43], v[168:171], v[206:209], v[40:43]
	v_mfma_f32_16x16x32_bf16 v[36:39], v[172:175], v[188:191], v[36:39]
	v_mfma_f32_16x16x32_bf16 v[36:39], v[176:179], v[206:209], v[36:39]
	v_mfma_f32_16x16x32_bf16 v[24:27], v[164:167], v[210:213], v[24:27]
	v_mfma_f32_16x16x32_bf16 v[24:27], v[168:171], v[224:227], v[24:27]
	v_mfma_f32_16x16x32_bf16 v[20:23], v[172:175], v[210:213], v[20:23]
	v_mfma_f32_16x16x32_bf16 v[20:23], v[176:179], v[224:227], v[20:23]
	v_mfma_f32_16x16x32_bf16 v[8:11], v[164:167], v[228:231], v[8:11]
	v_mfma_f32_16x16x32_bf16 v[8:11], v[168:171], v[240:243], v[8:11]
	v_mfma_f32_16x16x32_bf16 v[4:7], v[172:175], v[228:231], v[4:7]
	v_mfma_f32_16x16x32_bf16 v[4:7], v[176:179], v[240:243], v[4:7]
	s_barrier
	s_add_i32 s59, 0, 0x18000
	v_add_u32_e32 v142, s59, v143
	s_add_i32 s60, 0, 0x1c000
	ds_read_b128 v[144:147], v142
	ds_read_b128 v[152:155], v142 offset:1024
	ds_read_b128 v[156:159], v142 offset:2048
	ds_read_b128 v[160:163], v142 offset:3072
	v_add_u32_e32 v142, s60, v143
	ds_read_b128 v[164:167], v142
	ds_read_b128 v[168:171], v142 offset:1024
	ds_read_b128 v[172:175], v142 offset:2048
	ds_read_b128 v[176:179], v142 offset:3072
	s_add_u32 s18, s18, 0x100000
	s_addc_u32 s19, s19, 0
	s_mov_b32 m0, s54
	v_lshl_add_u64 v[248:249], s[18:19], 0, v[136:137]
	ds_read_b128 v[180:183], v151 offset:32768
	ds_read_b128 v[184:187], v151 offset:33792
	ds_read_b128 v[188:191], v151 offset:34816
	ds_read_b128 v[206:209], v151 offset:35840
	ds_read_b128 v[210:213], v151 offset:36864
	ds_read_b128 v[224:227], v151 offset:37888
	ds_read_b128 v[228:231], v151 offset:38912
	ds_read_b128 v[240:243], v151 offset:39936
	global_load_lds_dwordx4 v[248:249], off
	v_lshl_add_u64 v[248:249], s[18:19], 0, v[134:135]
	s_mov_b32 m0, s55
	s_nop 0
	global_load_lds_dwordx4 v[248:249], off
	s_waitcnt vmcnt(8)
	s_waitcnt lgkmcnt(0)
	s_barrier
	s_waitcnt lgkmcnt(0)
	v_mfma_f32_16x16x32_bf16 v[128:131], v[144:147], v[180:183], v[128:131]
	v_mfma_f32_16x16x32_bf16 v[128:131], v[152:155], v[184:187], v[128:131]
	v_mfma_f32_16x16x32_bf16 v[124:127], v[156:159], v[180:183], v[124:127]
	v_mfma_f32_16x16x32_bf16 v[124:127], v[160:163], v[184:187], v[124:127]
	v_mfma_f32_16x16x32_bf16 v[112:115], v[144:147], v[188:191], v[112:115]
	v_mfma_f32_16x16x32_bf16 v[112:115], v[152:155], v[206:209], v[112:115]
	v_mfma_f32_16x16x32_bf16 v[108:111], v[156:159], v[188:191], v[108:111]
	v_mfma_f32_16x16x32_bf16 v[108:111], v[160:163], v[206:209], v[108:111]
	v_mfma_f32_16x16x32_bf16 v[96:99], v[144:147], v[210:213], v[96:99]
	v_mfma_f32_16x16x32_bf16 v[96:99], v[152:155], v[224:227], v[96:99]
	v_mfma_f32_16x16x32_bf16 v[92:95], v[156:159], v[210:213], v[92:95]
	v_mfma_f32_16x16x32_bf16 v[92:95], v[160:163], v[224:227], v[92:95]
	v_mfma_f32_16x16x32_bf16 v[80:83], v[144:147], v[228:231], v[80:83]
	v_mfma_f32_16x16x32_bf16 v[80:83], v[152:155], v[240:243], v[80:83]
	v_mfma_f32_16x16x32_bf16 v[76:79], v[156:159], v[228:231], v[76:79]
	v_mfma_f32_16x16x32_bf16 v[76:79], v[160:163], v[240:243], v[76:79]
	v_mfma_f32_16x16x32_bf16 v[120:123], v[164:167], v[180:183], v[120:123]
	v_mfma_f32_16x16x32_bf16 v[120:123], v[168:171], v[184:187], v[120:123]
	v_mfma_f32_16x16x32_bf16 v[116:119], v[172:175], v[180:183], v[116:119]
	v_mfma_f32_16x16x32_bf16 v[116:119], v[176:179], v[184:187], v[116:119]
	v_mfma_f32_16x16x32_bf16 v[104:107], v[164:167], v[188:191], v[104:107]
	v_mfma_f32_16x16x32_bf16 v[104:107], v[168:171], v[206:209], v[104:107]
	v_mfma_f32_16x16x32_bf16 v[100:103], v[172:175], v[188:191], v[100:103]
	v_mfma_f32_16x16x32_bf16 v[100:103], v[176:179], v[206:209], v[100:103]
	v_mfma_f32_16x16x32_bf16 v[88:91], v[164:167], v[210:213], v[88:91]
	v_mfma_f32_16x16x32_bf16 v[88:91], v[168:171], v[224:227], v[88:91]
	v_mfma_f32_16x16x32_bf16 v[84:87], v[172:175], v[210:213], v[84:87]
	v_mfma_f32_16x16x32_bf16 v[84:87], v[176:179], v[224:227], v[84:87]
	v_mfma_f32_16x16x32_bf16 v[72:75], v[164:167], v[228:231], v[72:75]
	v_mfma_f32_16x16x32_bf16 v[72:75], v[168:171], v[240:243], v[72:75]
	v_mfma_f32_16x16x32_bf16 v[68:71], v[172:175], v[228:231], v[68:71]
	v_mfma_f32_16x16x32_bf16 v[68:71], v[176:179], v[240:243], v[68:71]
	s_barrier
	s_add_i32 s18, s59, s35
	v_lshl_add_u64 v[192:193], v[192:193], 0, s[4:5]
	s_mov_b32 m0, s18
	ds_read_b128 v[180:183], v151 offset:49152
	ds_read_b128 v[184:187], v151 offset:50176
	ds_read_b128 v[188:191], v151 offset:51200
	ds_read_b128 v[206:209], v151 offset:52224
	ds_read_b128 v[210:213], v151 offset:53248
	ds_read_b128 v[224:227], v151 offset:54272
	ds_read_b128 v[228:231], v151 offset:55296
	ds_read_b128 v[240:243], v151 offset:56320
	global_load_lds_dwordx4 v[192:193], off
	s_add_i32 m0, s18, 0x2000
	s_add_u32 s14, s14, 0x100080
	v_lshl_add_u64 v[192:193], v[214:215], 0, s[4:5]
	s_addc_u32 s15, s15, 0
	s_add_i32 s18, s60, s35
	global_load_lds_dwordx4 v[192:193], off
	v_lshl_add_u64 v[192:193], s[14:15], 0, v[2:3]
	s_mov_b32 m0, s18
	s_nop 0
	global_load_lds_dwordx4 v[192:193], off
	v_lshl_add_u64 v[192:193], s[14:15], 0, v[132:133]
	s_add_i32 m0, s18, 0x2000
	s_nop 0
	global_load_lds_dwordx4 v[192:193], off
	v_lshl_add_u64 v[192:193], v[244:245], 0, s[4:5]
	s_mov_b32 m0, s56
	s_nop 0
	global_load_lds_dwordx4 v[192:193], off
	v_lshl_add_u64 v[192:193], v[246:247], 0, s[4:5]
	s_mov_b32 m0, s57
	s_nop 0
	global_load_lds_dwordx4 v[192:193], off
	s_waitcnt vmcnt(8)
	s_waitcnt lgkmcnt(0)
	s_barrier
	s_waitcnt lgkmcnt(0)
	v_mfma_f32_16x16x32_bf16 v[64:67], v[144:147], v[180:183], v[64:67]
	v_mfma_f32_16x16x32_bf16 v[64:67], v[152:155], v[184:187], v[64:67]
	v_mfma_f32_16x16x32_bf16 v[60:63], v[156:159], v[180:183], v[60:63]
	v_mfma_f32_16x16x32_bf16 v[60:63], v[160:163], v[184:187], v[60:63]
	v_mfma_f32_16x16x32_bf16 v[48:51], v[144:147], v[188:191], v[48:51]
	v_mfma_f32_16x16x32_bf16 v[48:51], v[152:155], v[206:209], v[48:51]
	v_mfma_f32_16x16x32_bf16 v[44:47], v[156:159], v[188:191], v[44:47]
	v_mfma_f32_16x16x32_bf16 v[44:47], v[160:163], v[206:209], v[44:47]
	v_mfma_f32_16x16x32_bf16 v[32:35], v[144:147], v[210:213], v[32:35]
	v_mfma_f32_16x16x32_bf16 v[32:35], v[152:155], v[224:227], v[32:35]
	v_mfma_f32_16x16x32_bf16 v[28:31], v[156:159], v[210:213], v[28:31]
	v_mfma_f32_16x16x32_bf16 v[28:31], v[160:163], v[224:227], v[28:31]
	v_mfma_f32_16x16x32_bf16 v[16:19], v[144:147], v[228:231], v[16:19]
	v_mfma_f32_16x16x32_bf16 v[16:19], v[152:155], v[240:243], v[16:19]
	v_mfma_f32_16x16x32_bf16 v[12:15], v[156:159], v[228:231], v[12:15]
	v_mfma_f32_16x16x32_bf16 v[12:15], v[160:163], v[240:243], v[12:15]
	v_mfma_f32_16x16x32_bf16 v[56:59], v[164:167], v[180:183], v[56:59]
	v_mfma_f32_16x16x32_bf16 v[56:59], v[168:171], v[184:187], v[56:59]
	v_mfma_f32_16x16x32_bf16 v[52:55], v[172:175], v[180:183], v[52:55]
	v_mfma_f32_16x16x32_bf16 v[52:55], v[176:179], v[184:187], v[52:55]
	v_mfma_f32_16x16x32_bf16 v[40:43], v[164:167], v[188:191], v[40:43]
	v_mfma_f32_16x16x32_bf16 v[40:43], v[168:171], v[206:209], v[40:43]
	v_mfma_f32_16x16x32_bf16 v[36:39], v[172:175], v[188:191], v[36:39]
	v_mfma_f32_16x16x32_bf16 v[36:39], v[176:179], v[206:209], v[36:39]
	v_mfma_f32_16x16x32_bf16 v[24:27], v[164:167], v[210:213], v[24:27]
	v_mfma_f32_16x16x32_bf16 v[24:27], v[168:171], v[224:227], v[24:27]
	v_mfma_f32_16x16x32_bf16 v[20:23], v[172:175], v[210:213], v[20:23]
	v_mfma_f32_16x16x32_bf16 v[20:23], v[176:179], v[224:227], v[20:23]
	v_mfma_f32_16x16x32_bf16 v[8:11], v[164:167], v[228:231], v[8:11]
	v_mfma_f32_16x16x32_bf16 v[8:11], v[168:171], v[240:243], v[8:11]
	v_mfma_f32_16x16x32_bf16 v[4:7], v[172:175], v[228:231], v[4:7]
	v_mfma_f32_16x16x32_bf16 v[4:7], v[176:179], v[240:243], v[4:7]
	s_barrier
	s_add_i32 s47, s47, 2
	s_add_u32 s52, s52, 0x100
	s_addc_u32 s53, s53, 0
	s_add_u32 s29, s29, 0x100
	s_addc_u32 s45, s45, 0
	s_cmp_gt_u32 s47, 61
	s_cbranch_scc0 .LBB0_1158
	s_and_b64 vcc, exec, s[42:43]
	s_cbranch_vccz .LBB0_1161
	s_barrier

.LBB0_1236:
	s_add_u32 s56, s14, 0x10000
	v_mov_b32_e32 v4, 0
	s_addc_u32 s57, s15, 0
	s_mov_b32 s58, -2
	s_waitcnt lgkmcnt(0)
	v_mov_b32_e32 v5, v4
	v_mov_b64_e32 v[6:7], v[4:5]
	v_mov_b64_e32 v[8:9], v[4:5]
	v_mov_b64_e32 v[10:11], v[4:5]
	v_mov_b64_e32 v[12:13], v[4:5]
	v_mov_b64_e32 v[14:15], v[4:5]
	v_mov_b64_e32 v[16:17], v[4:5]
	v_mov_b64_e32 v[18:19], v[4:5]
	v_mov_b64_e32 v[20:21], v[4:5]
	v_mov_b64_e32 v[22:23], v[4:5]
	v_mov_b64_e32 v[24:25], v[4:5]
	v_mov_b64_e32 v[26:27], v[4:5]
	v_mov_b64_e32 v[28:29], v[4:5]
	v_mov_b64_e32 v[30:31], v[4:5]
	v_mov_b64_e32 v[32:33], v[4:5]
	v_mov_b64_e32 v[34:35], v[4:5]
	v_mov_b64_e32 v[36:37], v[4:5]
	v_mov_b64_e32 v[38:39], v[4:5]
	v_mov_b64_e32 v[40:41], v[4:5]
	v_mov_b64_e32 v[42:43], v[4:5]
	v_mov_b64_e32 v[44:45], v[4:5]
	v_mov_b64_e32 v[46:47], v[4:5]
	v_mov_b64_e32 v[48:49], v[4:5]
	v_mov_b64_e32 v[50:51], v[4:5]
	v_mov_b64_e32 v[52:53], v[4:5]
	v_mov_b64_e32 v[54:55], v[4:5]
	v_mov_b64_e32 v[56:57], v[4:5]
	v_mov_b64_e32 v[58:59], v[4:5]
	v_mov_b64_e32 v[64:65], v[4:5]
	v_mov_b64_e32 v[66:67], v[4:5]
	v_mov_b64_e32 v[72:73], v[4:5]
	v_mov_b64_e32 v[74:75], v[4:5]
	v_mov_b64_e32 v[84:85], v[4:5]
	v_mov_b64_e32 v[86:87], v[4:5]
	v_mov_b64_e32 v[88:89], v[4:5]
	v_mov_b64_e32 v[90:91], v[4:5]
	v_mov_b64_e32 v[92:93], v[4:5]
	v_mov_b64_e32 v[94:95], v[4:5]
	v_mov_b64_e32 v[96:97], v[4:5]
	v_mov_b64_e32 v[98:99], v[4:5]
	v_mov_b64_e32 v[100:101], v[4:5]
	v_mov_b64_e32 v[102:103], v[4:5]
	v_mov_b64_e32 v[104:105], v[4:5]
	v_mov_b64_e32 v[106:107], v[4:5]
	v_mov_b64_e32 v[108:109], v[4:5]
	v_mov_b64_e32 v[110:111], v[4:5]
	v_mov_b64_e32 v[112:113], v[4:5]
	v_mov_b64_e32 v[114:115], v[4:5]
	v_mov_b64_e32 v[116:117], v[4:5]
	v_mov_b64_e32 v[118:119], v[4:5]
	v_mov_b64_e32 v[120:121], v[4:5]
	v_mov_b64_e32 v[122:123], v[4:5]
	v_mov_b64_e32 v[124:125], v[4:5]
	v_mov_b64_e32 v[126:127], v[4:5]
	v_mov_b64_e32 v[128:129], v[4:5]
	v_mov_b64_e32 v[130:131], v[4:5]
	v_mov_b64_e32 v[132:133], v[4:5]
	v_mov_b64_e32 v[134:135], v[4:5]
	v_mov_b64_e32 v[136:137], v[4:5]
	v_mov_b64_e32 v[138:139], v[4:5]
	v_mov_b64_e32 v[140:141], v[4:5]
	v_mov_b64_e32 v[142:143], v[4:5]
	v_mov_b64_e32 v[144:145], v[4:5]
	v_mov_b64_e32 v[146:147], v[4:5]
.LBB0_1237:
	s_add_u32 s14, s52, 0x10000
	s_addc_u32 s15, s53, 0
	s_add_i32 s59, 0, 0x10000
	s_cmpk_eq_i32 s58, 0xa8
	s_cselect_b32 s25, s43, s15
	s_cselect_b32 s24, s42, s14
	s_cselect_b32 s19, s47, s57
	s_cselect_b32 s18, s46, s56
	s_add_i32 s60, 0, 0x14000
	v_add_u32_e32 v80, s59, v197
	v_add_u32_e32 v160, s60, v197
	ds_read_b128 v[60:63], v80
	ds_read_b128 v[68:71], v80 offset:1024
	ds_read_b128 v[76:79], v80 offset:2048
	ds_read_b128 v[80:83], v80 offset:3072
	ds_read_b128 v[148:151], v160
	ds_read_b128 v[152:155], v160 offset:1024
	ds_read_b128 v[156:159], v160 offset:2048
	ds_read_b128 v[160:163], v160 offset:3072
	v_lshl_add_u64 v[184:185], s[52:53], 0, v[188:189]
	s_add_i32 m0, s28, 0xc000
	ds_read_b128 v[164:167], v241
	ds_read_b128 v[168:171], v241 offset:1024
	ds_read_b128 v[172:175], v241 offset:2048
	ds_read_b128 v[176:179], v241 offset:3072
	ds_read_b128 v[180:183], v241 offset:4096
	ds_read_b128 v[206:209], v241 offset:5120
	ds_read_b128 v[210:213], v241 offset:6144
	ds_read_b128 v[224:227], v241 offset:7168
	global_load_lds_dwordx4 v[184:185], off
	v_lshl_add_u64 v[184:185], s[52:53], 0, v[190:191]
	s_add_i32 m0, s28, 0xe000
	s_nop 0
	global_load_lds_dwordx4 v[184:185], off
	s_waitcnt vmcnt(8)
	s_waitcnt lgkmcnt(0)
	s_barrier
	s_waitcnt lgkmcnt(0)
	v_mfma_f32_16x16x32_bf16 v[144:147], v[60:63], v[164:167], v[144:147]
	v_mfma_f32_16x16x32_bf16 v[144:147], v[68:71], v[168:171], v[144:147]
	v_mfma_f32_16x16x32_bf16 v[140:143], v[76:79], v[164:167], v[140:143]
	v_mfma_f32_16x16x32_bf16 v[140:143], v[80:83], v[168:171], v[140:143]
	v_mfma_f32_16x16x32_bf16 v[128:131], v[60:63], v[172:175], v[128:131]
	v_mfma_f32_16x16x32_bf16 v[128:131], v[68:71], v[176:179], v[128:131]
	v_mfma_f32_16x16x32_bf16 v[124:127], v[76:79], v[172:175], v[124:127]
	v_mfma_f32_16x16x32_bf16 v[124:127], v[80:83], v[176:179], v[124:127]
	v_mfma_f32_16x16x32_bf16 v[112:115], v[60:63], v[180:183], v[112:115]
	v_mfma_f32_16x16x32_bf16 v[112:115], v[68:71], v[206:209], v[112:115]
	v_mfma_f32_16x16x32_bf16 v[108:111], v[76:79], v[180:183], v[108:111]
	v_mfma_f32_16x16x32_bf16 v[108:111], v[80:83], v[206:209], v[108:111]
	v_mfma_f32_16x16x32_bf16 v[96:99], v[60:63], v[210:213], v[96:99]
	v_mfma_f32_16x16x32_bf16 v[96:99], v[68:71], v[224:227], v[96:99]
	v_mfma_f32_16x16x32_bf16 v[92:95], v[76:79], v[210:213], v[92:95]
	v_mfma_f32_16x16x32_bf16 v[92:95], v[80:83], v[224:227], v[92:95]
	v_mfma_f32_16x16x32_bf16 v[136:139], v[148:151], v[164:167], v[136:139]
	v_mfma_f32_16x16x32_bf16 v[136:139], v[152:155], v[168:171], v[136:139]
	v_mfma_f32_16x16x32_bf16 v[132:135], v[156:159], v[164:167], v[132:135]
	v_mfma_f32_16x16x32_bf16 v[132:135], v[160:163], v[168:171], v[132:135]
	v_mfma_f32_16x16x32_bf16 v[120:123], v[148:151], v[172:175], v[120:123]
	v_mfma_f32_16x16x32_bf16 v[120:123], v[152:155], v[176:179], v[120:123]
	v_mfma_f32_16x16x32_bf16 v[116:119], v[156:159], v[172:175], v[116:119]
	v_mfma_f32_16x16x32_bf16 v[116:119], v[160:163], v[176:179], v[116:119]
	v_mfma_f32_16x16x32_bf16 v[104:107], v[148:151], v[180:183], v[104:107]
	v_mfma_f32_16x16x32_bf16 v[104:107], v[152:155], v[206:209], v[104:107]
	v_mfma_f32_16x16x32_bf16 v[100:103], v[156:159], v[180:183], v[100:103]
	v_mfma_f32_16x16x32_bf16 v[100:103], v[160:163], v[206:209], v[100:103]
	v_mfma_f32_16x16x32_bf16 v[88:91], v[148:151], v[210:213], v[88:91]
	v_mfma_f32_16x16x32_bf16 v[88:91], v[152:155], v[224:227], v[88:91]
	v_mfma_f32_16x16x32_bf16 v[84:87], v[156:159], v[210:213], v[84:87]
	v_mfma_f32_16x16x32_bf16 v[84:87], v[160:163], v[224:227], v[84:87]
	s_barrier
	s_add_i32 s52, s59, s27
	v_lshl_add_u64 v[184:185], s[18:19], 0, v[2:3]
	s_mov_b32 m0, s52
	ds_read_b128 v[164:167], v241 offset:16384
	ds_read_b128 v[168:171], v241 offset:17408
	ds_read_b128 v[172:175], v241 offset:18432
	ds_read_b128 v[176:179], v241 offset:19456
	ds_read_b128 v[180:183], v241 offset:20480
	ds_read_b128 v[206:209], v241 offset:21504
	ds_read_b128 v[210:213], v241 offset:22528
	ds_read_b128 v[224:227], v241 offset:23552
	global_load_lds_dwordx4 v[184:185], off
	s_add_i32 m0, s52, 0x2000
	s_add_u32 s52, s18, 0x4000
	v_lshl_add_u64 v[192:193], s[18:19], 0, v[186:187]
	s_addc_u32 s53, s19, 0
	s_add_i32 s59, s60, s27
	global_load_lds_dwordx4 v[192:193], off
	v_lshl_add_u64 v[214:215], s[52:53], 0, v[2:3]
	s_mov_b32 m0, s59
	v_lshl_add_u64 v[228:229], s[24:25], 0, v[186:187]
	global_load_lds_dwordx4 v[214:215], off
	v_lshl_add_u64 v[214:215], s[52:53], 0, v[186:187]
	s_add_i32 m0, s59, 0x2000
	s_nop 0
	global_load_lds_dwordx4 v[214:215], off
	v_lshl_add_u64 v[214:215], s[24:25], 0, v[2:3]
	s_mov_b32 m0, s28
	s_nop 0
	global_load_lds_dwordx4 v[214:215], off
	s_mov_b32 m0, s29
	s_nop 0
	global_load_lds_dwordx4 v[228:229], off
	s_waitcnt vmcnt(8)
	s_waitcnt lgkmcnt(0)
	s_barrier
	s_waitcnt lgkmcnt(0)
	v_mfma_f32_16x16x32_bf16 v[72:75], v[60:63], v[164:167], v[72:75]
	v_mfma_f32_16x16x32_bf16 v[72:75], v[68:71], v[168:171], v[72:75]
	v_mfma_f32_16x16x32_bf16 v[64:67], v[76:79], v[164:167], v[64:67]
	v_mfma_f32_16x16x32_bf16 v[64:67], v[80:83], v[168:171], v[64:67]
	v_mfma_f32_16x16x32_bf16 v[48:51], v[60:63], v[172:175], v[48:51]
	v_mfma_f32_16x16x32_bf16 v[48:51], v[68:71], v[176:179], v[48:51]
	v_mfma_f32_16x16x32_bf16 v[44:47], v[76:79], v[172:175], v[44:47]
	v_mfma_f32_16x16x32_bf16 v[44:47], v[80:83], v[176:179], v[44:47]
	v_mfma_f32_16x16x32_bf16 v[32:35], v[60:63], v[180:183], v[32:35]
	v_mfma_f32_16x16x32_bf16 v[32:35], v[68:71], v[206:209], v[32:35]
	v_mfma_f32_16x16x32_bf16 v[28:31], v[76:79], v[180:183], v[28:31]
	v_mfma_f32_16x16x32_bf16 v[28:31], v[80:83], v[206:209], v[28:31]
	v_mfma_f32_16x16x32_bf16 v[16:19], v[60:63], v[210:213], v[16:19]
	v_mfma_f32_16x16x32_bf16 v[16:19], v[68:71], v[224:227], v[16:19]
	v_mfma_f32_16x16x32_bf16 v[12:15], v[76:79], v[210:213], v[12:15]
	v_mfma_f32_16x16x32_bf16 v[12:15], v[80:83], v[224:227], v[12:15]
	v_mfma_f32_16x16x32_bf16 v[56:59], v[148:151], v[164:167], v[56:59]
	v_mfma_f32_16x16x32_bf16 v[56:59], v[152:155], v[168:171], v[56:59]
	v_mfma_f32_16x16x32_bf16 v[52:55], v[156:159], v[164:167], v[52:55]
	v_mfma_f32_16x16x32_bf16 v[52:55], v[160:163], v[168:171], v[52:55]
	v_mfma_f32_16x16x32_bf16 v[40:43], v[148:151], v[172:175], v[40:43]
	v_mfma_f32_16x16x32_bf16 v[40:43], v[152:155], v[176:179], v[40:43]
	v_mfma_f32_16x16x32_bf16 v[36:39], v[156:159], v[172:175], v[36:39]
	v_mfma_f32_16x16x32_bf16 v[36:39], v[160:163], v[176:179], v[36:39]
	v_mfma_f32_16x16x32_bf16 v[24:27], v[148:151], v[180:183], v[24:27]
	v_mfma_f32_16x16x32_bf16 v[24:27], v[152:155], v[206:209], v[24:27]
	v_mfma_f32_16x16x32_bf16 v[20:23], v[156:159], v[180:183], v[20:23]
	v_mfma_f32_16x16x32_bf16 v[20:23], v[160:163], v[206:209], v[20:23]
	v_mfma_f32_16x16x32_bf16 v[8:11], v[148:151], v[210:213], v[8:11]
	v_mfma_f32_16x16x32_bf16 v[8:11], v[152:155], v[224:227], v[8:11]
	v_mfma_f32_16x16x32_bf16 v[4:7], v[156:159], v[210:213], v[4:7]
	v_mfma_f32_16x16x32_bf16 v[4:7], v[160:163], v[224:227], v[4:7]
	s_barrier
	s_add_i32 s52, 0, 0x18000
	s_add_i32 s53, 0, 0x1c000
	v_add_u32_e32 v80, s52, v197
	v_add_u32_e32 v160, s53, v197
	ds_read_b128 v[60:63], v80
	ds_read_b128 v[68:71], v80 offset:1024
	ds_read_b128 v[76:79], v80 offset:2048
	ds_read_b128 v[80:83], v80 offset:3072
	ds_read_b128 v[148:151], v160
	ds_read_b128 v[152:155], v160 offset:1024
	ds_read_b128 v[156:159], v160 offset:2048
	ds_read_b128 v[160:163], v160 offset:3072
	s_add_u32 s24, s24, 0x4000
	s_addc_u32 s25, s25, 0
	s_mov_b32 m0, s30
	v_lshl_add_u64 v[230:231], s[24:25], 0, v[2:3]
	ds_read_b128 v[164:167], v241 offset:32768
	ds_read_b128 v[168:171], v241 offset:33792
	ds_read_b128 v[172:175], v241 offset:34816
	ds_read_b128 v[176:179], v241 offset:35840
	ds_read_b128 v[180:183], v241 offset:36864
	ds_read_b128 v[206:209], v241 offset:37888
	ds_read_b128 v[210:213], v241 offset:38912
	ds_read_b128 v[224:227], v241 offset:39936
	global_load_lds_dwordx4 v[230:231], off
	v_lshl_add_u64 v[230:231], s[24:25], 0, v[186:187]
	s_mov_b32 m0, s31
	s_nop 0
	global_load_lds_dwordx4 v[230:231], off
	s_waitcnt vmcnt(8)
	s_waitcnt lgkmcnt(0)
	s_barrier
	s_waitcnt lgkmcnt(0)
	v_mfma_f32_16x16x32_bf16 v[144:147], v[60:63], v[164:167], v[144:147]
	v_mfma_f32_16x16x32_bf16 v[144:147], v[68:71], v[168:171], v[144:147]
	v_mfma_f32_16x16x32_bf16 v[140:143], v[76:79], v[164:167], v[140:143]
	v_mfma_f32_16x16x32_bf16 v[140:143], v[80:83], v[168:171], v[140:143]
	v_mfma_f32_16x16x32_bf16 v[128:131], v[60:63], v[172:175], v[128:131]
	v_mfma_f32_16x16x32_bf16 v[128:131], v[68:71], v[176:179], v[128:131]
	v_mfma_f32_16x16x32_bf16 v[124:127], v[76:79], v[172:175], v[124:127]
	v_mfma_f32_16x16x32_bf16 v[124:127], v[80:83], v[176:179], v[124:127]
	v_mfma_f32_16x16x32_bf16 v[112:115], v[60:63], v[180:183], v[112:115]
	v_mfma_f32_16x16x32_bf16 v[112:115], v[68:71], v[206:209], v[112:115]
	v_mfma_f32_16x16x32_bf16 v[108:111], v[76:79], v[180:183], v[108:111]
	v_mfma_f32_16x16x32_bf16 v[108:111], v[80:83], v[206:209], v[108:111]
	v_mfma_f32_16x16x32_bf16 v[96:99], v[60:63], v[210:213], v[96:99]
	v_mfma_f32_16x16x32_bf16 v[96:99], v[68:71], v[224:227], v[96:99]
	v_mfma_f32_16x16x32_bf16 v[92:95], v[76:79], v[210:213], v[92:95]
	v_mfma_f32_16x16x32_bf16 v[92:95], v[80:83], v[224:227], v[92:95]
	v_mfma_f32_16x16x32_bf16 v[136:139], v[148:151], v[164:167], v[136:139]
	v_mfma_f32_16x16x32_bf16 v[136:139], v[152:155], v[168:171], v[136:139]
	v_mfma_f32_16x16x32_bf16 v[132:135], v[156:159], v[164:167], v[132:135]
	v_mfma_f32_16x16x32_bf16 v[132:135], v[160:163], v[168:171], v[132:135]
	v_mfma_f32_16x16x32_bf16 v[120:123], v[148:151], v[172:175], v[120:123]
	v_mfma_f32_16x16x32_bf16 v[120:123], v[152:155], v[176:179], v[120:123]
	v_mfma_f32_16x16x32_bf16 v[116:119], v[156:159], v[172:175], v[116:119]
	v_mfma_f32_16x16x32_bf16 v[116:119], v[160:163], v[176:179], v[116:119]
	v_mfma_f32_16x16x32_bf16 v[104:107], v[148:151], v[180:183], v[104:107]
	v_mfma_f32_16x16x32_bf16 v[104:107], v[152:155], v[206:209], v[104:107]
	v_mfma_f32_16x16x32_bf16 v[100:103], v[156:159], v[180:183], v[100:103]
	v_mfma_f32_16x16x32_bf16 v[100:103], v[160:163], v[206:209], v[100:103]
	v_mfma_f32_16x16x32_bf16 v[88:91], v[148:151], v[210:213], v[88:91]
	v_mfma_f32_16x16x32_bf16 v[88:91], v[152:155], v[224:227], v[88:91]
	v_mfma_f32_16x16x32_bf16 v[84:87], v[156:159], v[210:213], v[84:87]
	v_mfma_f32_16x16x32_bf16 v[84:87], v[160:163], v[224:227], v[84:87]
	s_barrier
	s_add_i32 s24, s52, s27
	v_lshl_add_u64 v[184:185], v[184:185], 0, s[96:97]
	s_mov_b32 m0, s24
	ds_read_b128 v[164:167], v241 offset:49152
	ds_read_b128 v[168:171], v241 offset:50176
	ds_read_b128 v[172:175], v241 offset:51200
	ds_read_b128 v[176:179], v241 offset:52224
	ds_read_b128 v[180:183], v241 offset:53248
	ds_read_b128 v[206:209], v241 offset:54272
	ds_read_b128 v[210:213], v241 offset:55296
	ds_read_b128 v[224:227], v241 offset:56320
	global_load_lds_dwordx4 v[184:185], off
	s_add_i32 m0, s24, 0x2000
	s_add_u32 s18, s18, 0xc000
	v_lshl_add_u64 v[184:185], v[192:193], 0, s[96:97]
	s_addc_u32 s19, s19, 0
	s_add_i32 s24, s53, s27
	global_load_lds_dwordx4 v[184:185], off
	v_lshl_add_u64 v[184:185], s[18:19], 0, v[2:3]
	s_mov_b32 m0, s24
	s_nop 0
	global_load_lds_dwordx4 v[184:185], off
	v_lshl_add_u64 v[184:185], s[18:19], 0, v[186:187]
	s_add_i32 m0, s24, 0x2000
	s_nop 0
	global_load_lds_dwordx4 v[184:185], off
	v_lshl_add_u64 v[184:185], v[214:215], 0, s[96:97]
	s_mov_b32 m0, s35
	s_nop 0
	global_load_lds_dwordx4 v[184:185], off
	v_lshl_add_u64 v[184:185], v[228:229], 0, s[96:97]
	s_mov_b32 m0, s36
	s_nop 0
	global_load_lds_dwordx4 v[184:185], off
	s_waitcnt vmcnt(8)
	s_waitcnt lgkmcnt(0)
	s_barrier
	s_waitcnt lgkmcnt(0)
	v_mfma_f32_16x16x32_bf16 v[72:75], v[60:63], v[164:167], v[72:75]
	v_mfma_f32_16x16x32_bf16 v[72:75], v[68:71], v[168:171], v[72:75]
	v_mfma_f32_16x16x32_bf16 v[64:67], v[76:79], v[164:167], v[64:67]
	v_mfma_f32_16x16x32_bf16 v[64:67], v[80:83], v[168:171], v[64:67]
	v_mfma_f32_16x16x32_bf16 v[48:51], v[60:63], v[172:175], v[48:51]
	v_mfma_f32_16x16x32_bf16 v[48:51], v[68:71], v[176:179], v[48:51]
	v_mfma_f32_16x16x32_bf16 v[44:47], v[76:79], v[172:175], v[44:47]
	v_mfma_f32_16x16x32_bf16 v[44:47], v[80:83], v[176:179], v[44:47]
	v_mfma_f32_16x16x32_bf16 v[32:35], v[60:63], v[180:183], v[32:35]
	v_mfma_f32_16x16x32_bf16 v[32:35], v[68:71], v[206:209], v[32:35]
	v_mfma_f32_16x16x32_bf16 v[28:31], v[76:79], v[180:183], v[28:31]
	v_mfma_f32_16x16x32_bf16 v[28:31], v[80:83], v[206:209], v[28:31]
	v_mfma_f32_16x16x32_bf16 v[16:19], v[60:63], v[210:213], v[16:19]
	v_mfma_f32_16x16x32_bf16 v[16:19], v[68:71], v[224:227], v[16:19]
	v_mfma_f32_16x16x32_bf16 v[12:15], v[76:79], v[210:213], v[12:15]
	v_mfma_f32_16x16x32_bf16 v[12:15], v[80:83], v[224:227], v[12:15]
	v_mfma_f32_16x16x32_bf16 v[56:59], v[148:151], v[164:167], v[56:59]
	v_mfma_f32_16x16x32_bf16 v[56:59], v[152:155], v[168:171], v[56:59]
	v_mfma_f32_16x16x32_bf16 v[52:55], v[156:159], v[164:167], v[52:55]
	v_mfma_f32_16x16x32_bf16 v[52:55], v[160:163], v[168:171], v[52:55]
	v_mfma_f32_16x16x32_bf16 v[40:43], v[148:151], v[172:175], v[40:43]
	v_mfma_f32_16x16x32_bf16 v[40:43], v[152:155], v[176:179], v[40:43]
	v_mfma_f32_16x16x32_bf16 v[36:39], v[156:159], v[172:175], v[36:39]
	v_mfma_f32_16x16x32_bf16 v[36:39], v[160:163], v[176:179], v[36:39]
	v_mfma_f32_16x16x32_bf16 v[24:27], v[148:151], v[180:183], v[24:27]
	v_mfma_f32_16x16x32_bf16 v[24:27], v[152:155], v[206:209], v[24:27]
	v_mfma_f32_16x16x32_bf16 v[20:23], v[156:159], v[180:183], v[20:23]
	v_mfma_f32_16x16x32_bf16 v[20:23], v[160:163], v[206:209], v[20:23]
	v_mfma_f32_16x16x32_bf16 v[8:11], v[148:151], v[210:213], v[8:11]
	v_mfma_f32_16x16x32_bf16 v[8:11], v[152:155], v[224:227], v[8:11]
	v_mfma_f32_16x16x32_bf16 v[4:7], v[156:159], v[210:213], v[4:7]
	v_mfma_f32_16x16x32_bf16 v[4:7], v[160:163], v[224:227], v[4:7]
	s_barrier
	s_add_i32 s58, s58, 2
	s_add_u32 s56, s56, 0x10000
	s_addc_u32 s57, s57, 0
	s_cmpk_gt_u32 s58, 0xa9
	s_mov_b64 s[52:53], s[14:15]
	s_cbranch_scc0 .LBB0_1237
	s_and_b64 vcc, exec, s[44:45]
	s_cbranch_vccz .LBB0_1240
	s_barrier
